# MA: ds_bpermute xor-shuffles replaced by DPP / v_permlane16,32_swap (no LDS round trips) on top of v11
# speedup vs baseline: 1.0144x; 1.0144x over previous
; #define GAS __attribute__((address_space(1)))
; __device__ __forceinline__ float shx(float v, int o, int lane) { return __builtin_bit_cast(float, __builtin_amdgcn_ds_bpermute((lane ^ o) << 2, __builtin_bit_cast(int, v))); }
; __device__ __forceinline__ float wave_sum(float v, int lane) {
; #pragma unroll
;     for (int o = 1; o < 64; o <<= 1) v += shx(v, o, lane);
;     return v;
; __device__ __forceinline__ void phase_ma(const Params& p, Frame& F, int l, const bool fd, const float* xin32) {
;     ...
;             for (int j = 0; j < 4; ++j) { if (!fd) { const v2u xw = *(const GAS v2u*)(xb + (size_t)row * D + 256 * j + 4 * F.lane); h[r][j] = (f32x4){bf_lo(xw.x), bf_hi(xw.x), bf_lo(xw.y), bf_hi(xw.y)}; } ss += (h[r][j].x * h[r][j].x + h[r][j].y * h[r][j].y) + (h[r][j].z * h[r][j].z + h[r][j].w * h[r][j].w); }
;             rs[r] = ss; }
; #pragma unroll
;         for (int r = 0; r < 4; ++r) { const int row = b * S + s0 + r * rstep; const float rstd = rsqrtf(wave_sum(rs[r], F.lane) * (1.0f / D) + EPS);
.LBB0_840:
	v_mul_f32_e32 v32, v99, v99
	v_mul_f32_e32 v33, v121, v121
	v_fmac_f32_e32 v32, v98, v98
	v_fmac_f32_e32 v33, v120, v120
	v_add_f32_e32 v32, v32, v33
	v_mul_f32_e32 v33, v91, v91
	s_waitcnt lgkmcnt(0)
	v_mul_f32_e32 v34, v119, v119
	v_fmac_f32_e32 v33, v90, v90
	v_fmac_f32_e32 v34, v118, v118
	v_add_f32_e32 v33, v33, v34
	v_add_f32_e32 v32, v32, v33
	v_mul_f32_e32 v33, v89, v89
	v_mul_f32_e32 v34, v109, v109
	v_fmac_f32_e32 v33, v88, v88
	v_fmac_f32_e32 v34, v108, v108
	v_add_f32_e32 v33, v33, v34
	v_add_f32_e32 v32, v32, v33
	v_mul_f32_e32 v33, v87, v87
	v_mul_f32_e32 v34, v117, v117
	v_fmac_f32_e32 v33, v86, v86
	v_fmac_f32_e32 v34, v116, v116
	v_add_f32_e32 v33, v33, v34
	v_mul_f32_e32 v34, v83, v83
	v_mul_f32_e32 v35, v107, v107
	v_fmac_f32_e32 v34, v82, v82
	v_fmac_f32_e32 v35, v106, v106
	v_add_f32_e32 v34, v34, v35
	v_add_f32_e32 v33, v33, v34
	v_mul_f32_e32 v34, v81, v81
	v_mul_f32_e32 v35, v101, v101
	v_fmac_f32_e32 v34, v80, v80
	v_fmac_f32_e32 v35, v100, v100
	v_add_f32_e32 v34, v34, v35
	v_add_f32_e32 v33, v33, v34
	v_mul_f32_e32 v34, v115, v115
	v_mul_f32_e32 v35, v129, v129
	v_fmac_f32_e32 v34, v114, v114
	v_fmac_f32_e32 v35, v128, v128
	v_add_f32_e32 v34, v34, v35
	v_add_f32_e32 v33, v33, v34
	v_mul_f32_e32 v34, v77, v77
	v_mul_f32_e32 v35, v111, v111
	v_fmac_f32_e32 v34, v76, v76
	v_fmac_f32_e32 v35, v110, v110
	v_add_f32_e32 v34, v34, v35
	v_mul_f32_e32 v35, v75, v75
	v_mul_f32_e32 v36, v103, v103
	v_fmac_f32_e32 v35, v74, v74
	v_fmac_f32_e32 v36, v102, v102
	v_add_f32_e32 v35, v35, v36
	v_add_f32_e32 v34, v34, v35
	v_mul_f32_e32 v35, v73, v73
	v_mul_f32_e32 v36, v93, v93
	v_fmac_f32_e32 v35, v72, v72
	v_fmac_f32_e32 v36, v92, v92
	v_add_f32_e32 v35, v35, v36
	v_add_f32_e32 v34, v34, v35
	v_mul_f32_e32 v35, v95, v95
	v_mul_f32_e32 v36, v125, v125
	v_fmac_f32_e32 v35, v94, v94
	v_fmac_f32_e32 v36, v124, v124
	v_add_f32_e32 v35, v35, v36
	v_add_f32_e32 v34, v34, v35
	v_mul_f32_e32 v35, v79, v79
	v_mul_f32_e32 v36, v113, v113
	v_fmac_f32_e32 v35, v78, v78
	v_fmac_f32_e32 v36, v112, v112
	v_add_f32_e32 v35, v35, v36
	v_mul_f32_e32 v36, v71, v71
	v_mul_f32_e32 v37, v105, v105
	v_fmac_f32_e32 v36, v70, v70
	v_fmac_f32_e32 v37, v104, v104
	v_add_f32_e32 v36, v36, v37
	v_add_f32_e32 v35, v35, v36
	v_mul_f32_e32 v36, v69, v69
	v_mul_f32_e32 v37, v97, v97
	v_fmac_f32_e32 v36, v68, v68
	v_fmac_f32_e32 v37, v96, v96
	v_add_f32_e32 v36, v36, v37
	v_add_f32_e32 v35, v35, v36
	v_mul_f32_e32 v36, v85, v85
	v_mul_f32_e32 v37, v127, v127
	v_fmac_f32_e32 v36, v84, v84
	v_fmac_f32_e32 v37, v126, v126
	v_add_f32_e32 v36, v36, v37
	v_add_f32_e32 v35, v35, v36
	v_pk_mul_f32 v[36:37], v[130:131], v[130:131]
	v_pk_mul_f32 v[38:39], v[122:123], v[122:123]
	s_mov_b32 s2, 0x358637bd
	v_pk_mov_b32 v[140:141], v[38:39], v[36:37] op_sel:[1,0]
	v_mov_b32_e32 v39, v37
	v_pk_add_f32 v[36:37], v[140:141], v[38:39]
	s_mov_b32 s18, 0x3a800000
	v_add_f32_e32 v36, v36, v37
	v_add_f32_e32 v32, v32, v36
	v_mov_b32_dpp v37, v35 quad_perm:[1,0,3,2] row_mask:0xf bank_mask:0xf
	v_mov_b32_dpp v36, v34 quad_perm:[1,0,3,2] row_mask:0xf bank_mask:0xf
	v_lshl_add_u64 v[38:39], v[60:61], 0, s[8:9]
	s_mov_b32 s8, 0x800000
	s_waitcnt lgkmcnt(0)
	v_pk_add_f32 v[34:35], v[34:35], v[36:37]
	s_nop 1
	v_mov_b32_dpp v37, v35 quad_perm:[2,3,0,1] row_mask:0xf bank_mask:0xf
	v_mov_b32_dpp v36, v34 quad_perm:[2,3,0,1] row_mask:0xf bank_mask:0xf
	s_waitcnt lgkmcnt(0)
	v_pk_add_f32 v[34:35], v[34:35], v[36:37]
	s_nop 1
	v_mov_b32_dpp v37, v35 quad_perm:[3,2,1,0] row_mask:0xf bank_mask:0xf
	s_nop 1
	v_mov_b32_dpp v37, v37 row_half_mirror row_mask:0xf bank_mask:0xf
	v_mov_b32_dpp v36, v34 quad_perm:[3,2,1,0] row_mask:0xf bank_mask:0xf
	s_nop 1
	v_mov_b32_dpp v36, v36 row_half_mirror row_mask:0xf bank_mask:0xf
	s_waitcnt lgkmcnt(0)
	v_pk_add_f32 v[34:35], v[34:35], v[36:37]
	s_nop 1
	v_mov_b32_dpp v37, v35 row_ror:8 row_mask:0xf bank_mask:0xf
	v_mov_b32_dpp v36, v34 row_ror:8 row_mask:0xf bank_mask:0xf
	s_waitcnt lgkmcnt(0)
	v_pk_add_f32 v[34:35], v[34:35], v[36:37]
	v_mov_b32_e32 v37, v35
	s_nop 1
	v_permlane16_swap_b32 v37, v35
	v_mov_b32_e32 v36, v34
	s_nop 1
	v_permlane16_swap_b32 v36, v34
	s_waitcnt lgkmcnt(0)
	v_pk_add_f32 v[34:35], v[34:35], v[36:37]
	v_mov_b32_e32 v37, v35
	s_nop 1
	v_permlane32_swap_b32 v37, v35
	v_mov_b32_e32 v36, v34
	s_nop 1
	v_permlane32_swap_b32 v36, v34
	s_waitcnt lgkmcnt(0)
; #define GAS __attribute__((address_space(1)))
; __device__ __forceinline__ unsigned pk2(float lo, float hi) { const f32x2_t v = {lo, hi}; return __builtin_bit_cast(unsigned, __builtin_convertvector(v, bf16x2_t)); }
; __device__ __forceinline__ float shx(float v, int o, int lane) { return __builtin_bit_cast(float, __builtin_amdgcn_ds_bpermute((lane ^ o) << 2, __builtin_bit_cast(int, v))); }
; __device__ __forceinline__ float wave_sum(float v, int lane) {
; #pragma unroll
;     for (int o = 1; o < 64; o <<= 1) v += shx(v, o, lane);
;     return v;
; __device__ __forceinline__ void phase_ma(const Params& p, Frame& F, int l, const bool fd, const float* xin32) {
;     ...
;         for (int r = 0; r < 4; ++r) { const int row = b * S + s0 + r * rstep; const float rstd = rsqrtf(wave_sum(rs[r], F.lane) * (1.0f / D) + EPS);
; #pragma unroll
;             for (int j = 0; j < 4; ++j) { h[r][j] = h[r][j] * rstd * Av[j] + Bv[j];
;                 v2u o; o.x = pk2(h[r][j].x, h[r][j].y); o.y = pk2(h[r][j].z, h[r][j].w); *(GAS v2u*)(H + (size_t)row * D + 256 * j + 4 * F.lane) = o; } }
	v_pk_add_f32 v[36:37], v[34:35], v[36:37]
	v_mov_b64_e32 v[34:35], s[2:3]
	v_pk_fma_f32 v[36:37], v[36:37], s[18:19], v[34:35] op_sel_hi:[1,0,0]
	s_nop 0
	v_mul_f32_e32 v139, 0x4b800000, v37
	v_cmp_gt_f32_e64 s[2:3], s8, v37
	v_cmp_gt_f32_e32 vcc, s8, v36
	s_nop 0
	v_cndmask_b32_e64 v37, v37, v139, s[2:3]
	v_rsq_f32_e32 v37, v37
	s_nop 0
	v_mul_f32_e32 v139, 0x45800000, v37
	v_cndmask_b32_e64 v140, v37, v139, s[2:3]
	v_mul_f32_e32 v37, 0x4b800000, v36
	v_cndmask_b32_e32 v36, v36, v37, vcc
	v_rsq_f32_e32 v36, v36
	v_pk_mul_f32 v[78:79], v[140:141], v[78:79] op_sel_hi:[0,1]
	v_pk_mul_f32 v[112:113], v[140:141], v[112:113] op_sel_hi:[0,1]
	v_pk_fma_f32 v[112:113], v[58:59], v[112:113], v[10:11]
	v_pk_fma_f32 v[78:79], v[56:57], v[78:79], v[8:9]
	v_pk_mul_f32 v[70:71], v[140:141], v[70:71] op_sel_hi:[0,1]
	v_pk_mul_f32 v[104:105], v[140:141], v[104:105] op_sel_hi:[0,1]
	v_cvt_pk_bf16_f32 v142, v78, v79
	v_cvt_pk_bf16_f32 v143, v112, v113
	v_pk_fma_f32 v[104:105], v[50:51], v[104:105], v[2:3]
	v_pk_fma_f32 v[70:71], v[48:49], v[70:71], v[0:1]
	v_pk_mul_f32 v[68:69], v[140:141], v[68:69] op_sel_hi:[0,1]
	v_pk_mul_f32 v[96:97], v[140:141], v[96:97] op_sel_hi:[0,1]
	v_pk_mul_f32 v[84:85], v[140:141], v[84:85] op_sel_hi:[0,1]
	v_pk_mul_f32 v[126:127], v[140:141], v[126:127] op_sel_hi:[0,1]
	global_store_dwordx2 v[38:39], v[142:143], off
	v_cvt_pk_bf16_f32 v142, v70, v71
	v_cvt_pk_bf16_f32 v143, v104, v105
	v_pk_fma_f32 v[96:97], v[44:45], v[96:97], v[6:7]
	v_pk_fma_f32 v[68:69], v[46:47], v[68:69], v[4:5]
	v_pk_fma_f32 v[126:127], v[40:41], v[126:127], v[14:15]
	v_pk_fma_f32 v[84:85], v[42:43], v[84:85], v[12:13]
	v_mul_f32_e32 v37, 0x45800000, v36
	global_store_dwordx2 v[38:39], v[142:143], off offset:512
	v_cvt_pk_bf16_f32 v142, v68, v69
	v_cvt_pk_bf16_f32 v143, v96, v97
	v_cvt_pk_bf16_f32 v140, v84, v85
	v_cvt_pk_bf16_f32 v141, v126, v127
	v_cndmask_b32_e32 v36, v36, v37, vcc
	global_store_dwordx2 v[38:39], v[142:143], off offset:1024
	global_store_dwordx2 v[38:39], v[140:141], off offset:1536
	v_pk_mul_f32 v[38:39], v[36:37], v[76:77] op_sel_hi:[0,1]
	v_pk_mul_f32 v[76:77], v[36:37], v[110:111] op_sel_hi:[0,1]
	v_pk_fma_f32 v[110:111], v[58:59], v[76:77], v[10:11]
	v_pk_fma_f32 v[76:77], v[56:57], v[38:39], v[8:9]
	v_cvt_pk_bf16_f32 v39, v110, v111
	v_cvt_pk_bf16_f32 v38, v76, v77
	v_lshl_add_u64 v[140:141], v[60:61], 0, s[12:13]
	global_store_dwordx2 v[140:141], v[38:39], off
	v_pk_mul_f32 v[38:39], v[36:37], v[74:75] op_sel_hi:[0,1]
	v_pk_mul_f32 v[74:75], v[36:37], v[102:103] op_sel_hi:[0,1]
	v_pk_fma_f32 v[102:103], v[50:51], v[74:75], v[2:3]
	v_pk_fma_f32 v[74:75], v[48:49], v[38:39], v[0:1]
	v_cvt_pk_bf16_f32 v39, v102, v103
	v_cvt_pk_bf16_f32 v38, v74, v75
	global_store_dwordx2 v[140:141], v[38:39], off offset:512
	v_pk_mul_f32 v[38:39], v[36:37], v[72:73] op_sel_hi:[0,1]
	v_pk_mul_f32 v[72:73], v[36:37], v[92:93] op_sel_hi:[0,1]
	v_pk_fma_f32 v[92:93], v[44:45], v[72:73], v[6:7]
	v_pk_fma_f32 v[72:73], v[46:47], v[38:39], v[4:5]
	v_cvt_pk_bf16_f32 v39, v92, v93
	v_cvt_pk_bf16_f32 v38, v72, v73
	global_store_dwordx2 v[140:141], v[38:39], off offset:1024
	v_pk_mul_f32 v[38:39], v[36:37], v[94:95] op_sel_hi:[0,1]
	v_pk_mul_f32 v[36:37], v[36:37], v[124:125] op_sel_hi:[0,1]
	v_pk_fma_f32 v[124:125], v[40:41], v[36:37], v[14:15]
	v_pk_fma_f32 v[94:95], v[42:43], v[38:39], v[12:13]
	v_cvt_pk_bf16_f32 v37, v124, v125
	v_cvt_pk_bf16_f32 v36, v94, v95
	global_store_dwordx2 v[140:141], v[36:37], off offset:1536
	v_mov_b32_dpp v37, v33 quad_perm:[1,0,3,2] row_mask:0xf bank_mask:0xf
	v_mov_b32_dpp v36, v32 quad_perm:[1,0,3,2] row_mask:0xf bank_mask:0xf
	v_lshl_add_u64 v[38:39], v[60:61], 0, s[14:15]
	s_waitcnt lgkmcnt(0)
	v_pk_add_f32 v[32:33], v[32:33], v[36:37]
	s_nop 1
	v_mov_b32_dpp v37, v33 quad_perm:[2,3,0,1] row_mask:0xf bank_mask:0xf
	v_mov_b32_dpp v36, v32 quad_perm:[2,3,0,1] row_mask:0xf bank_mask:0xf
	s_waitcnt lgkmcnt(0)
	v_pk_add_f32 v[32:33], v[32:33], v[36:37]
	s_nop 1
	v_mov_b32_dpp v37, v33 quad_perm:[3,2,1,0] row_mask:0xf bank_mask:0xf
	s_nop 1
	v_mov_b32_dpp v37, v37 row_half_mirror row_mask:0xf bank_mask:0xf
	v_mov_b32_dpp v36, v32 quad_perm:[3,2,1,0] row_mask:0xf bank_mask:0xf
	s_nop 1
	v_mov_b32_dpp v36, v36 row_half_mirror row_mask:0xf bank_mask:0xf
	s_waitcnt lgkmcnt(0)
	v_pk_add_f32 v[32:33], v[32:33], v[36:37]
	s_nop 1
	v_mov_b32_dpp v37, v33 row_ror:8 row_mask:0xf bank_mask:0xf
	v_mov_b32_dpp v36, v32 row_ror:8 row_mask:0xf bank_mask:0xf
	s_waitcnt lgkmcnt(0)
	v_pk_add_f32 v[32:33], v[32:33], v[36:37]
	v_mov_b32_e32 v37, v33
	s_nop 1
	v_permlane16_swap_b32 v37, v33
	v_mov_b32_e32 v36, v32
	s_nop 1
	v_permlane16_swap_b32 v36, v32
	s_waitcnt lgkmcnt(0)
	v_pk_add_f32 v[32:33], v[32:33], v[36:37]
	v_mov_b32_e32 v37, v33
	s_nop 1
	v_permlane32_swap_b32 v37, v33
	v_mov_b32_e32 v36, v32
	s_nop 1
	v_permlane32_swap_b32 v36, v32
	s_waitcnt lgkmcnt(0)
; #define GAS __attribute__((address_space(1)))
; #define LAS __attribute__((address_space(3)))
; __device__ __forceinline__ unsigned pk2(float lo, float hi) { const f32x2_t v = {lo, hi}; return __builtin_bit_cast(unsigned, __builtin_convertvector(v, bf16x2_t)); }
; __device__ __forceinline__ void phase_ma(const Params& p, Frame& F, int l, const bool fd, const float* xin32) {
;     ...
;         for (int r = 0; r < 4; ++r) { const int row = b * S + s0 + r * rstep; const float rstd = rsqrtf(wave_sum(rs[r], F.lane) * (1.0f / D) + EPS);
; #pragma unroll
;             for (int j = 0; j < 4; ++j) { h[r][j] = h[r][j] * rstd * Av[j] + Bv[j];
;                 v2u o; o.x = pk2(h[r][j].x, h[r][j].y); o.y = pk2(h[r][j].z, h[r][j].w); *(GAS v2u*)(H + (size_t)row * D + 256 * j + 4 * F.lane) = o; } }
;         float th2[4][2];
; #pragma unroll
;         for (int hh = 0; hh < 2; ++hh) {
;             asm volatile("" ::: "memory");
;             float v[4][8];
; #pragma unroll
;             for (int ei = 0; ei < 8; ++ei) { const int e = 8 * hh + ei; float a0 = 0.f, a1 = 0.f, a2 = 0.f, a3 = 0.f;
; #pragma unroll
;                 for (int j = 0; j < 4; ++j) { const LAS float* w = wrp + (((e * 4 + j) * 4) << 6) + F.lane; const float w0 = w[0], w1 = w[64], w2 = w[128], w3 = w[192];
;                     a0 += h[0][j].x * w0 + h[0][j].y * w1 + h[0][j].z * w2 + h[0][j].w * w3; a1 += h[1][j].x * w0 + h[1][j].y * w1 + h[1][j].z * w2 + h[1][j].w * w3;
;                     a2 += h[2][j].x * w0 + h[2][j].y * w1 + h[2][j].z * w2 + h[2][j].w * w3; a3 += h[3][j].x * w0 + h[3][j].y * w1 + h[3][j].z * w2 + h[3][j].w * w3; }
	v_pk_add_f32 v[32:33], v[32:33], v[36:37]
	s_nop 0
	v_pk_fma_f32 v[32:33], v[32:33], s[18:19], v[34:35] op_sel_hi:[1,0,0]
	s_nop 0
	v_mul_f32_e32 v34, 0x4b800000, v33
	v_cmp_gt_f32_e64 s[2:3], s8, v33
	v_cmp_gt_f32_e32 vcc, s8, v32
	s_nop 0
	v_cndmask_b32_e64 v33, v33, v34, s[2:3]
	v_rsq_f32_e32 v33, v33
	s_nop 0
	v_mul_f32_e32 v34, 0x45800000, v33
	v_cndmask_b32_e64 v34, v33, v34, s[2:3]
	v_pk_mul_f32 v[36:37], v[34:35], v[86:87] op_sel_hi:[0,1]
	v_pk_mul_f32 v[86:87], v[34:35], v[116:117] op_sel_hi:[0,1]
	v_pk_fma_f32 v[116:117], v[58:59], v[86:87], v[10:11]
	v_pk_fma_f32 v[86:87], v[56:57], v[36:37], v[8:9]
	v_cvt_pk_bf16_f32 v37, v116, v117
	v_cvt_pk_bf16_f32 v36, v86, v87
	global_store_dwordx2 v[38:39], v[36:37], off
	v_pk_mul_f32 v[36:37], v[34:35], v[82:83] op_sel_hi:[0,1]
	v_pk_mul_f32 v[82:83], v[34:35], v[106:107] op_sel_hi:[0,1]
	v_pk_fma_f32 v[106:107], v[50:51], v[82:83], v[2:3]
	v_pk_fma_f32 v[82:83], v[48:49], v[36:37], v[0:1]
	v_mul_f32_e32 v33, 0x4b800000, v32
	v_cvt_pk_bf16_f32 v36, v82, v83
	v_cvt_pk_bf16_f32 v37, v106, v107
	v_cndmask_b32_e32 v32, v32, v33, vcc
	global_store_dwordx2 v[38:39], v[36:37], off offset:512
	v_pk_mul_f32 v[36:37], v[34:35], v[80:81] op_sel_hi:[0,1]
	v_pk_mul_f32 v[80:81], v[34:35], v[100:101] op_sel_hi:[0,1]
	v_rsq_f32_e32 v32, v32
	v_pk_fma_f32 v[100:101], v[44:45], v[80:81], v[6:7]
	v_pk_fma_f32 v[80:81], v[46:47], v[36:37], v[4:5]
	v_cvt_pk_bf16_f32 v37, v100, v101
	v_cvt_pk_bf16_f32 v36, v80, v81
	global_store_dwordx2 v[38:39], v[36:37], off offset:1024
	v_pk_mul_f32 v[36:37], v[34:35], v[114:115] op_sel_hi:[0,1]
	v_pk_mul_f32 v[34:35], v[34:35], v[128:129] op_sel_hi:[0,1]
	v_pk_fma_f32 v[128:129], v[40:41], v[34:35], v[14:15]
	v_pk_fma_f32 v[114:115], v[42:43], v[36:37], v[12:13]
	v_mul_f32_e32 v33, 0x45800000, v32
	v_cvt_pk_bf16_f32 v34, v114, v115
	v_cvt_pk_bf16_f32 v35, v128, v129
	v_cndmask_b32_e32 v32, v32, v33, vcc
	global_store_dwordx2 v[38:39], v[34:35], off offset:1536
	v_pk_mul_f32 v[34:35], v[32:33], v[98:99] op_sel_hi:[0,1]
	v_pk_mul_f32 v[36:37], v[32:33], v[120:121] op_sel_hi:[0,1]
	v_pk_fma_f32 v[120:121], v[58:59], v[36:37], v[10:11]
	v_pk_fma_f32 v[98:99], v[56:57], v[34:35], v[8:9]
	v_cvt_pk_bf16_f32 v35, v120, v121
	v_cvt_pk_bf16_f32 v34, v98, v99
	v_lshl_add_u64 v[36:37], v[60:61], 0, s[16:17]
	global_store_dwordx2 v[36:37], v[34:35], off
	v_pk_mul_f32 v[34:35], v[32:33], v[90:91] op_sel_hi:[0,1]
	v_pk_mul_f32 v[38:39], v[32:33], v[118:119] op_sel_hi:[0,1]
	v_pk_fma_f32 v[118:119], v[50:51], v[38:39], v[2:3]
	v_pk_fma_f32 v[90:91], v[48:49], v[34:35], v[0:1]
	v_cvt_pk_bf16_f32 v35, v118, v119
	v_cvt_pk_bf16_f32 v34, v90, v91
	global_store_dwordx2 v[36:37], v[34:35], off offset:512
	v_pk_mul_f32 v[34:35], v[32:33], v[88:89] op_sel_hi:[0,1]
	v_pk_mul_f32 v[38:39], v[32:33], v[108:109] op_sel_hi:[0,1]
	v_pk_fma_f32 v[108:109], v[44:45], v[38:39], v[6:7]
	v_pk_fma_f32 v[88:89], v[46:47], v[34:35], v[4:5]
	v_cvt_pk_bf16_f32 v35, v108, v109
	v_cvt_pk_bf16_f32 v34, v88, v89
	global_store_dwordx2 v[36:37], v[34:35], off offset:1024
	v_pk_mul_f32 v[34:35], v[32:33], v[122:123] op_sel_hi:[0,1]
	v_pk_mul_f32 v[32:33], v[32:33], v[130:131] op_sel_hi:[0,1]
	v_pk_fma_f32 v[130:131], v[40:41], v[32:33], v[14:15]
	v_pk_fma_f32 v[122:123], v[42:43], v[34:35], v[12:13]
	v_cvt_pk_bf16_f32 v33, v130, v131
	v_cvt_pk_bf16_f32 v32, v122, v123
	global_store_dwordx2 v[36:37], v[32:33], off offset:1536
	ds_read2st64_b32 v[32:33], v138 offset1:1
	ds_read2st64_b32 v[34:35], v138 offset0:2 offset1:3
	s_mov_b32 s2, 0x3fb8aa3b
	s_waitcnt lgkmcnt(0)
	v_mul_f32_e32 v36, v79, v33
	v_mul_f32_e32 v37, v77, v33
	v_mul_f32_e32 v38, v87, v33
	v_mul_f32_e32 v33, v33, v99
	v_fmac_f32_e32 v33, v32, v98
	v_fmac_f32_e32 v36, v78, v32
	v_fmac_f32_e32 v37, v76, v32
	v_fmac_f32_e32 v38, v86, v32
	s_waitcnt lgkmcnt(0)
	v_fmac_f32_e32 v33, v34, v120
	v_fmac_f32_e32 v36, v112, v34
	v_fmac_f32_e32 v37, v110, v34
	v_fmac_f32_e32 v38, v116, v34
	v_fmac_f32_e32 v33, v35, v121
	v_fmac_f32_e32 v36, v113, v35
	v_fmac_f32_e32 v37, v111, v35
	v_fmac_f32_e32 v38, v117, v35
	v_add_f32_e32 v39, 0, v33
	ds_read2st64_b32 v[32:33], v138 offset0:4 offset1:5
	ds_read2st64_b32 v[34:35], v138 offset0:6 offset1:7
	v_add_f32_e32 v36, 0, v36
	v_add_f32_e32 v37, 0, v37
	v_add_f32_e32 v38, 0, v38
	s_waitcnt lgkmcnt(0)
	v_mul_f32_e32 v139, v71, v33
	v_fmac_f32_e32 v139, v70, v32
	s_waitcnt lgkmcnt(0)
	v_fmac_f32_e32 v139, v104, v34
	v_fmac_f32_e32 v139, v105, v35
	v_add_f32_e32 v36, v36, v139
	v_mul_f32_e32 v139, v75, v33
	v_fmac_f32_e32 v139, v74, v32
	v_fmac_f32_e32 v139, v102, v34
	v_fmac_f32_e32 v139, v103, v35
	v_add_f32_e32 v37, v37, v139
	v_mul_f32_e32 v139, v83, v33
	v_mul_f32_e32 v33, v33, v91
	v_fmac_f32_e32 v33, v32, v90
	v_fmac_f32_e32 v139, v82, v32
	v_fmac_f32_e32 v33, v34, v118
	v_fmac_f32_e32 v139, v106, v34
	v_fmac_f32_e32 v33, v35, v119
	v_fmac_f32_e32 v139, v107, v35
	v_add_f32_e32 v39, v33, v39
	ds_read2st64_b32 v[32:33], v138 offset0:8 offset1:9
	ds_read2st64_b32 v[34:35], v138 offset0:10 offset1:11
	v_add_f32_e32 v38, v38, v139
	s_waitcnt lgkmcnt(0)
	v_mul_f32_e32 v139, v69, v33
	v_fmac_f32_e32 v139, v68, v32
	s_waitcnt lgkmcnt(0)
	v_fmac_f32_e32 v139, v96, v34
	v_fmac_f32_e32 v139, v97, v35
	v_add_f32_e32 v139, v36, v139
	v_mul_f32_e32 v36, v73, v33
	v_fmac_f32_e32 v36, v72, v32
	v_fmac_f32_e32 v36, v92, v34
	v_fmac_f32_e32 v36, v93, v35
	v_add_f32_e32 v140, v37, v36
	v_mul_f32_e32 v36, v81, v33
	v_mul_f32_e32 v33, v33, v89
	v_fmac_f32_e32 v36, v80, v32
	v_fmac_f32_e32 v33, v32, v88
	v_fmac_f32_e32 v36, v100, v34
	v_fmac_f32_e32 v33, v108, v34
	v_fmac_f32_e32 v36, v101, v35
	v_fmac_f32_e32 v33, v109, v35
	v_add_f32_e32 v141, v38, v36
	v_add_f32_e32 v34, v33, v39
	ds_read2st64_b32 v[36:37], v138 offset0:12 offset1:13
	ds_read2st64_b32 v[38:39], v138 offset0:14 offset1:15
	s_waitcnt lgkmcnt(0)
; #define LAS __attribute__((address_space(3)))
; __device__ __forceinline__ void phase_ma(const Params& p, Frame& F, int l, const bool fd, const float* xin32) {
;     ...
;             for (int ei = 0; ei < 8; ++ei) { const int e = 8 * hh + ei; float a0 = 0.f, a1 = 0.f, a2 = 0.f, a3 = 0.f;
; #pragma unroll
;                 for (int j = 0; j < 4; ++j) { const LAS float* w = wrp + (((e * 4 + j) * 4) << 6) + F.lane; const float w0 = w[0], w1 = w[64], w2 = w[128], w3 = w[192];
;                     a0 += h[0][j].x * w0 + h[0][j].y * w1 + h[0][j].z * w2 + h[0][j].w * w3; a1 += h[1][j].x * w0 + h[1][j].y * w1 + h[1][j].z * w2 + h[1][j].w * w3;
;                     a2 += h[2][j].x * w0 + h[2][j].y * w1 + h[2][j].z * w2 + h[2][j].w * w3; a3 += h[3][j].x * w0 + h[3][j].y * w1 + h[3][j].z * w2 + h[3][j].w * w3; }
;                 v[0][ei] = a0; v[1][ei] = a1; v[2][ei] = a2; v[3][ei] = a3; }
	v_mul_f32_e32 v32, v85, v37
	v_fmac_f32_e32 v32, v84, v36
	s_waitcnt lgkmcnt(0)
	v_fmac_f32_e32 v32, v126, v38
	v_fmac_f32_e32 v32, v127, v39
	v_add_f32_e32 v33, v139, v32
	v_mul_f32_e32 v32, v95, v37
	v_mul_f32_e32 v35, v115, v37
	v_mul_f32_e32 v37, v123, v37
	v_fmac_f32_e32 v32, v94, v36
	v_fmac_f32_e32 v35, v114, v36
	v_fmac_f32_e32 v37, v122, v36
	v_fmac_f32_e32 v32, v124, v38
	v_fmac_f32_e32 v35, v128, v38
	v_fmac_f32_e32 v37, v130, v38
	v_fmac_f32_e32 v32, v125, v39
	v_fmac_f32_e32 v35, v129, v39
	v_fmac_f32_e32 v37, v131, v39
	v_add_f32_e32 v32, v140, v32
	v_add_f32_e32 v35, v141, v35
	v_add_f32_e32 v38, v34, v37
	ds_read2st64_b32 v[36:37], v138 offset0:16 offset1:17
	ds_read2st64_b32 v[140:141], v138 offset0:18 offset1:19
	s_waitcnt lgkmcnt(0)
	v_mul_f32_e32 v34, v79, v37
	v_mul_f32_e32 v39, v77, v37
	v_mul_f32_e32 v139, v87, v37
	v_mul_f32_e32 v37, v99, v37
	v_fmac_f32_e32 v37, v98, v36
	v_fmac_f32_e32 v34, v78, v36
	v_fmac_f32_e32 v39, v76, v36
	v_fmac_f32_e32 v139, v86, v36
	s_waitcnt lgkmcnt(0)
	v_fmac_f32_e32 v37, v120, v140
	v_fmac_f32_e32 v34, v112, v140
	v_fmac_f32_e32 v39, v110, v140
	v_fmac_f32_e32 v139, v116, v140
	v_fmac_f32_e32 v37, v121, v141
	v_fmac_f32_e32 v34, v113, v141
	v_fmac_f32_e32 v39, v111, v141
	v_fmac_f32_e32 v139, v117, v141
	v_add_f32_e32 v142, 0, v37
	ds_read2st64_b32 v[36:37], v138 offset0:20 offset1:21
	ds_read2st64_b32 v[140:141], v138 offset0:22 offset1:23
	v_add_f32_e32 v34, 0, v34
	v_add_f32_e32 v39, 0, v39
	v_add_f32_e32 v139, 0, v139
	s_waitcnt lgkmcnt(0)
	v_mul_f32_e32 v143, v71, v37
	v_fmac_f32_e32 v143, v70, v36
	s_waitcnt lgkmcnt(0)
	v_fmac_f32_e32 v143, v104, v140
	v_fmac_f32_e32 v143, v105, v141
	v_add_f32_e32 v34, v34, v143
	v_mul_f32_e32 v143, v75, v37
	v_fmac_f32_e32 v143, v74, v36
	v_fmac_f32_e32 v143, v102, v140
	v_fmac_f32_e32 v143, v103, v141
	v_add_f32_e32 v39, v39, v143
	v_mul_f32_e32 v143, v83, v37
	v_mul_f32_e32 v37, v91, v37
	v_fmac_f32_e32 v37, v90, v36
	v_fmac_f32_e32 v143, v82, v36
	v_fmac_f32_e32 v37, v118, v140
	v_fmac_f32_e32 v143, v106, v140
	v_fmac_f32_e32 v37, v119, v141
	v_fmac_f32_e32 v143, v107, v141
	v_add_f32_e32 v142, v142, v37
	ds_read2st64_b32 v[36:37], v138 offset0:24 offset1:25
	ds_read2st64_b32 v[140:141], v138 offset0:26 offset1:27
	v_add_f32_e32 v139, v139, v143
	s_waitcnt lgkmcnt(0)
	v_mul_f32_e32 v143, v69, v37
	v_fmac_f32_e32 v143, v68, v36
	s_waitcnt lgkmcnt(0)
	v_fmac_f32_e32 v143, v96, v140
	v_fmac_f32_e32 v143, v97, v141
	v_add_f32_e32 v34, v34, v143
	v_mul_f32_e32 v143, v73, v37
	v_fmac_f32_e32 v143, v72, v36
	v_fmac_f32_e32 v143, v92, v140
	v_fmac_f32_e32 v143, v93, v141
	v_add_f32_e32 v39, v39, v143
	v_mul_f32_e32 v143, v81, v37
	v_mul_f32_e32 v37, v89, v37
	v_fmac_f32_e32 v143, v80, v36
	v_fmac_f32_e32 v37, v88, v36
	v_fmac_f32_e32 v143, v100, v140
	v_fmac_f32_e32 v37, v108, v140
	v_fmac_f32_e32 v143, v101, v141
	v_fmac_f32_e32 v37, v109, v141
	v_add_f32_e32 v139, v139, v143
	v_add_f32_e32 v144, v142, v37
	ds_read2st64_b32 v[140:141], v138 offset0:28 offset1:29
	ds_read2st64_b32 v[142:143], v138 offset0:30 offset1:31
	s_waitcnt lgkmcnt(0)
	v_mul_f32_e32 v36, v85, v141
	v_fmac_f32_e32 v36, v84, v140
	s_waitcnt lgkmcnt(0)
	v_fmac_f32_e32 v36, v126, v142
	v_fmac_f32_e32 v36, v127, v143
	v_add_f32_e32 v37, v34, v36
	v_mul_f32_e32 v34, v95, v141
	v_fmac_f32_e32 v34, v94, v140
	v_fmac_f32_e32 v34, v124, v142
	v_fmac_f32_e32 v34, v125, v143
	v_add_f32_e32 v34, v39, v34
	v_mul_f32_e32 v36, v115, v141
	v_mul_f32_e32 v39, v123, v141
	v_fmac_f32_e32 v36, v114, v140
	v_fmac_f32_e32 v39, v122, v140
	v_fmac_f32_e32 v36, v128, v142
	v_fmac_f32_e32 v39, v130, v142
	v_fmac_f32_e32 v36, v129, v143
	v_fmac_f32_e32 v39, v131, v143
	ds_read2st64_b32 v[140:141], v138 offset0:32 offset1:33
	ds_read2st64_b32 v[142:143], v138 offset0:34 offset1:35
	v_add_f32_e32 v36, v139, v36
	v_add_f32_e32 v39, v144, v39
	s_waitcnt lgkmcnt(0)
	v_mul_f32_e32 v139, v79, v141
	v_mul_f32_e32 v144, v77, v141
	v_mul_f32_e32 v146, v87, v141
	v_mul_f32_e32 v141, v99, v141
	v_fmac_f32_e32 v141, v98, v140
	v_fmac_f32_e32 v139, v78, v140
	v_fmac_f32_e32 v144, v76, v140
	v_fmac_f32_e32 v146, v86, v140
	s_waitcnt lgkmcnt(0)
	v_fmac_f32_e32 v141, v120, v142
	v_fmac_f32_e32 v139, v112, v142
	v_fmac_f32_e32 v144, v110, v142
	v_fmac_f32_e32 v146, v116, v142
	v_fmac_f32_e32 v141, v121, v143
	v_fmac_f32_e32 v139, v113, v143
	v_fmac_f32_e32 v144, v111, v143
	v_fmac_f32_e32 v146, v117, v143
	v_add_f32_e32 v147, 0, v141
	ds_read2st64_b32 v[140:141], v138 offset0:36 offset1:37
	ds_read2st64_b32 v[142:143], v138 offset0:38 offset1:39
	v_add_f32_e32 v139, 0, v139
	v_add_f32_e32 v144, 0, v144
	v_add_f32_e32 v146, 0, v146
	s_waitcnt lgkmcnt(0)
	v_mul_f32_e32 v148, v71, v141
	v_fmac_f32_e32 v148, v70, v140
	s_waitcnt lgkmcnt(0)
	v_fmac_f32_e32 v148, v104, v142
	v_fmac_f32_e32 v148, v105, v143
	v_add_f32_e32 v139, v139, v148
	v_mul_f32_e32 v148, v75, v141
	v_fmac_f32_e32 v148, v74, v140
	v_fmac_f32_e32 v148, v102, v142
	v_fmac_f32_e32 v148, v103, v143
	v_add_f32_e32 v144, v144, v148
	v_mul_f32_e32 v148, v83, v141
	v_mul_f32_e32 v141, v91, v141
	v_fmac_f32_e32 v141, v90, v140
	v_fmac_f32_e32 v148, v82, v140
	v_fmac_f32_e32 v141, v118, v142
	v_fmac_f32_e32 v148, v106, v142
	v_fmac_f32_e32 v141, v119, v143
	v_fmac_f32_e32 v148, v107, v143
	v_add_f32_e32 v147, v147, v141
	ds_read2st64_b32 v[140:141], v138 offset0:40 offset1:41
	ds_read2st64_b32 v[142:143], v138 offset0:42 offset1:43
	v_add_f32_e32 v146, v146, v148
	s_waitcnt lgkmcnt(0)
	v_mul_f32_e32 v148, v69, v141
	v_fmac_f32_e32 v148, v68, v140
	s_waitcnt lgkmcnt(0)
; #define LAS __attribute__((address_space(3)))
; __device__ __forceinline__ void phase_ma(const Params& p, Frame& F, int l, const bool fd, const float* xin32) {
;     ...
;             for (int ei = 0; ei < 8; ++ei) { const int e = 8 * hh + ei; float a0 = 0.f, a1 = 0.f, a2 = 0.f, a3 = 0.f;
; #pragma unroll
;                 for (int j = 0; j < 4; ++j) { const LAS float* w = wrp + (((e * 4 + j) * 4) << 6) + F.lane; const float w0 = w[0], w1 = w[64], w2 = w[128], w3 = w[192];
;                     a0 += h[0][j].x * w0 + h[0][j].y * w1 + h[0][j].z * w2 + h[0][j].w * w3; a1 += h[1][j].x * w0 + h[1][j].y * w1 + h[1][j].z * w2 + h[1][j].w * w3;
;                     a2 += h[2][j].x * w0 + h[2][j].y * w1 + h[2][j].z * w2 + h[2][j].w * w3; a3 += h[3][j].x * w0 + h[3][j].y * w1 + h[3][j].z * w2 + h[3][j].w * w3; }
;                 v[0][ei] = a0; v[1][ei] = a1; v[2][ei] = a2; v[3][ei] = a3; }
	v_fmac_f32_e32 v148, v96, v142
	v_fmac_f32_e32 v148, v97, v143
	v_add_f32_e32 v139, v139, v148
	v_mul_f32_e32 v148, v73, v141
	v_fmac_f32_e32 v148, v72, v140
	v_fmac_f32_e32 v148, v92, v142
	v_fmac_f32_e32 v148, v93, v143
	v_add_f32_e32 v144, v144, v148
	v_mul_f32_e32 v148, v81, v141
	v_mul_f32_e32 v141, v89, v141
	v_fmac_f32_e32 v148, v80, v140
	v_fmac_f32_e32 v141, v88, v140
	v_fmac_f32_e32 v148, v100, v142
	v_fmac_f32_e32 v141, v108, v142
	v_fmac_f32_e32 v148, v101, v143
	v_fmac_f32_e32 v141, v109, v143
	v_add_f32_e32 v150, v146, v148
	v_add_f32_e32 v143, v147, v141
	ds_read2st64_b32 v[146:147], v138 offset0:44 offset1:45
	ds_read2st64_b32 v[148:149], v138 offset0:46 offset1:47
	s_waitcnt lgkmcnt(0)
	v_mul_f32_e32 v140, v85, v147
	v_fmac_f32_e32 v140, v84, v146
	s_waitcnt lgkmcnt(0)
	v_fmac_f32_e32 v140, v126, v148
	v_fmac_f32_e32 v140, v127, v149
	v_add_f32_e32 v140, v139, v140
	v_mul_f32_e32 v139, v95, v147
	v_fmac_f32_e32 v139, v94, v146
	v_fmac_f32_e32 v139, v124, v148
	v_fmac_f32_e32 v139, v125, v149
	v_add_f32_e32 v142, v144, v139
	v_mul_f32_e32 v139, v115, v147
	v_fmac_f32_e32 v139, v114, v146
	v_fmac_f32_e32 v139, v128, v148
	v_fmac_f32_e32 v139, v129, v149
	v_add_f32_e32 v141, v150, v139
	v_mul_f32_e32 v139, v123, v147
	v_fmac_f32_e32 v139, v122, v146
	v_fmac_f32_e32 v139, v130, v148
	v_fmac_f32_e32 v139, v131, v149
	ds_read2st64_b32 v[146:147], v138 offset0:48 offset1:49
	ds_read2st64_b32 v[148:149], v138 offset0:50 offset1:51
	v_add_f32_e32 v139, v143, v139
	s_waitcnt lgkmcnt(0)
	v_mul_f32_e32 v143, v79, v147
	v_mul_f32_e32 v144, v77, v147
	v_mul_f32_e32 v150, v87, v147
	v_mul_f32_e32 v147, v99, v147
	v_fmac_f32_e32 v147, v98, v146
	v_fmac_f32_e32 v143, v78, v146
	v_fmac_f32_e32 v144, v76, v146
	v_fmac_f32_e32 v150, v86, v146
	s_waitcnt lgkmcnt(0)
	v_fmac_f32_e32 v147, v120, v148
	v_fmac_f32_e32 v143, v112, v148
	v_fmac_f32_e32 v144, v110, v148
	v_fmac_f32_e32 v150, v116, v148
	v_fmac_f32_e32 v147, v121, v149
	v_fmac_f32_e32 v143, v113, v149
	v_fmac_f32_e32 v144, v111, v149
	v_fmac_f32_e32 v150, v117, v149
	v_add_f32_e32 v151, 0, v147
	ds_read2st64_b32 v[146:147], v138 offset0:52 offset1:53
	ds_read2st64_b32 v[148:149], v138 offset0:54 offset1:55
	v_add_f32_e32 v143, 0, v143
	v_add_f32_e32 v144, 0, v144
	v_add_f32_e32 v150, 0, v150
	s_waitcnt lgkmcnt(0)
	v_mul_f32_e32 v152, v71, v147
	v_fmac_f32_e32 v152, v70, v146
	s_waitcnt lgkmcnt(0)
	v_fmac_f32_e32 v152, v104, v148
	v_fmac_f32_e32 v152, v105, v149
	v_add_f32_e32 v143, v143, v152
	v_mul_f32_e32 v152, v75, v147
	v_fmac_f32_e32 v152, v74, v146
	v_fmac_f32_e32 v152, v102, v148
	v_fmac_f32_e32 v152, v103, v149
	v_add_f32_e32 v144, v144, v152
	v_mul_f32_e32 v152, v83, v147
	v_mul_f32_e32 v147, v91, v147
	v_fmac_f32_e32 v147, v90, v146
	v_fmac_f32_e32 v152, v82, v146
	v_fmac_f32_e32 v147, v118, v148
	v_fmac_f32_e32 v152, v106, v148
	v_fmac_f32_e32 v147, v119, v149
	v_fmac_f32_e32 v152, v107, v149
	v_add_f32_e32 v151, v151, v147
	ds_read2st64_b32 v[146:147], v138 offset0:56 offset1:57
	ds_read2st64_b32 v[148:149], v138 offset0:58 offset1:59
	v_add_f32_e32 v150, v150, v152
	s_waitcnt lgkmcnt(0)
	v_mul_f32_e32 v152, v69, v147
	v_fmac_f32_e32 v152, v68, v146
	s_waitcnt lgkmcnt(0)
	v_fmac_f32_e32 v152, v96, v148
	v_fmac_f32_e32 v152, v97, v149
	v_add_f32_e32 v143, v143, v152
	v_mul_f32_e32 v152, v73, v147
	v_fmac_f32_e32 v152, v72, v146
	v_fmac_f32_e32 v152, v92, v148
	v_fmac_f32_e32 v152, v93, v149
	v_add_f32_e32 v144, v144, v152
	v_mul_f32_e32 v152, v81, v147
	v_mul_f32_e32 v147, v89, v147
	v_fmac_f32_e32 v152, v80, v146
	v_fmac_f32_e32 v147, v88, v146
	v_fmac_f32_e32 v152, v100, v148
	v_fmac_f32_e32 v147, v108, v148
	v_fmac_f32_e32 v152, v101, v149
	v_fmac_f32_e32 v147, v109, v149
	v_add_f32_e32 v152, v150, v152
	v_add_f32_e32 v146, v151, v147
	ds_read2st64_b32 v[148:149], v138 offset0:60 offset1:61
	ds_read2st64_b32 v[150:151], v138 offset0:62 offset1:63
	s_waitcnt lgkmcnt(0)
	v_mul_f32_e32 v147, v85, v149
	v_fmac_f32_e32 v147, v84, v148
	s_waitcnt lgkmcnt(0)
	v_fmac_f32_e32 v147, v126, v150
	v_fmac_f32_e32 v147, v127, v151
	v_add_f32_e32 v156, v143, v147
	v_mul_f32_e32 v143, v95, v149
	v_fmac_f32_e32 v143, v94, v148
	v_fmac_f32_e32 v143, v124, v150
	v_fmac_f32_e32 v143, v125, v151
	v_add_f32_e32 v147, v144, v143
	v_mul_f32_e32 v143, v115, v149
	v_fmac_f32_e32 v143, v114, v148
	v_fmac_f32_e32 v143, v128, v150
	v_fmac_f32_e32 v143, v129, v151
	v_add_f32_e32 v144, v152, v143
	v_mul_f32_e32 v143, v123, v149
	v_fmac_f32_e32 v143, v122, v148
	v_fmac_f32_e32 v143, v130, v150
	v_fmac_f32_e32 v143, v131, v151
	ds_read2st64_b32 v[148:149], v138 offset0:64 offset1:65
	ds_read2st64_b32 v[150:151], v138 offset0:66 offset1:67
	v_add_f32_e32 v143, v146, v143
	s_waitcnt lgkmcnt(0)
	v_mul_f32_e32 v146, v79, v149
	v_mul_f32_e32 v152, v77, v149
	v_mul_f32_e32 v153, v87, v149
	v_mul_f32_e32 v149, v99, v149
	v_fmac_f32_e32 v149, v98, v148
	v_fmac_f32_e32 v146, v78, v148
	v_fmac_f32_e32 v152, v76, v148
	v_fmac_f32_e32 v153, v86, v148
	s_waitcnt lgkmcnt(0)
	v_fmac_f32_e32 v149, v120, v150
	v_fmac_f32_e32 v146, v112, v150
	v_fmac_f32_e32 v152, v110, v150
	v_fmac_f32_e32 v153, v116, v150
	v_fmac_f32_e32 v149, v121, v151
	v_fmac_f32_e32 v146, v113, v151
	v_fmac_f32_e32 v152, v111, v151
	v_fmac_f32_e32 v153, v117, v151
	v_add_f32_e32 v154, 0, v149
	ds_read2st64_b32 v[148:149], v138 offset0:68 offset1:69
	ds_read2st64_b32 v[150:151], v138 offset0:70 offset1:71
	v_add_f32_e32 v146, 0, v146
	v_add_f32_e32 v152, 0, v152
	v_add_f32_e32 v153, 0, v153
	s_waitcnt lgkmcnt(0)
	v_mul_f32_e32 v155, v71, v149
	v_fmac_f32_e32 v155, v70, v148
	s_waitcnt lgkmcnt(0)
; #define LAS __attribute__((address_space(3)))
; __device__ __forceinline__ void phase_ma(const Params& p, Frame& F, int l, const bool fd, const float* xin32) {
;     ...
;             for (int ei = 0; ei < 8; ++ei) { const int e = 8 * hh + ei; float a0 = 0.f, a1 = 0.f, a2 = 0.f, a3 = 0.f;
; #pragma unroll
;                 for (int j = 0; j < 4; ++j) { const LAS float* w = wrp + (((e * 4 + j) * 4) << 6) + F.lane; const float w0 = w[0], w1 = w[64], w2 = w[128], w3 = w[192];
;                     a0 += h[0][j].x * w0 + h[0][j].y * w1 + h[0][j].z * w2 + h[0][j].w * w3; a1 += h[1][j].x * w0 + h[1][j].y * w1 + h[1][j].z * w2 + h[1][j].w * w3;
;                     a2 += h[2][j].x * w0 + h[2][j].y * w1 + h[2][j].z * w2 + h[2][j].w * w3; a3 += h[3][j].x * w0 + h[3][j].y * w1 + h[3][j].z * w2 + h[3][j].w * w3; }
;                 v[0][ei] = a0; v[1][ei] = a1; v[2][ei] = a2; v[3][ei] = a3; }
	v_fmac_f32_e32 v155, v104, v150
	v_fmac_f32_e32 v155, v105, v151
	v_add_f32_e32 v146, v146, v155
	v_mul_f32_e32 v155, v75, v149
	v_fmac_f32_e32 v155, v74, v148
	v_fmac_f32_e32 v155, v102, v150
	v_fmac_f32_e32 v155, v103, v151
	v_add_f32_e32 v152, v152, v155
	v_mul_f32_e32 v155, v83, v149
	v_mul_f32_e32 v149, v91, v149
	v_fmac_f32_e32 v149, v90, v148
	v_fmac_f32_e32 v155, v82, v148
	v_fmac_f32_e32 v149, v118, v150
	v_fmac_f32_e32 v155, v106, v150
	v_fmac_f32_e32 v149, v119, v151
	v_fmac_f32_e32 v155, v107, v151
	v_add_f32_e32 v154, v154, v149
	ds_read2st64_b32 v[148:149], v138 offset0:72 offset1:73
	ds_read2st64_b32 v[150:151], v138 offset0:74 offset1:75
	v_add_f32_e32 v153, v153, v155
	s_waitcnt lgkmcnt(0)
	v_mul_f32_e32 v155, v69, v149
	v_fmac_f32_e32 v155, v68, v148
	s_waitcnt lgkmcnt(0)
	v_fmac_f32_e32 v155, v96, v150
	v_fmac_f32_e32 v155, v97, v151
	v_add_f32_e32 v146, v146, v155
	v_mul_f32_e32 v155, v73, v149
	v_fmac_f32_e32 v155, v72, v148
	v_fmac_f32_e32 v155, v92, v150
	v_fmac_f32_e32 v155, v93, v151
	v_add_f32_e32 v152, v152, v155
	v_mul_f32_e32 v155, v81, v149
	v_mul_f32_e32 v149, v89, v149
	v_fmac_f32_e32 v149, v88, v148
	v_fmac_f32_e32 v155, v80, v148
	v_fmac_f32_e32 v149, v108, v150
	v_fmac_f32_e32 v155, v100, v150
	v_fmac_f32_e32 v149, v109, v151
	v_fmac_f32_e32 v155, v101, v151
	v_add_f32_e32 v154, v154, v149
	ds_read2st64_b32 v[148:149], v138 offset0:76 offset1:77
	ds_read2st64_b32 v[150:151], v138 offset0:78 offset1:79
	v_add_f32_e32 v153, v153, v155
	s_waitcnt lgkmcnt(0)
	v_mul_f32_e32 v155, v85, v149
	v_fmac_f32_e32 v155, v84, v148
	s_waitcnt lgkmcnt(0)
	v_fmac_f32_e32 v155, v126, v150
	v_fmac_f32_e32 v155, v127, v151
	v_add_f32_e32 v165, v146, v155
	v_mul_f32_e32 v146, v95, v149
	v_fmac_f32_e32 v146, v94, v148
	v_fmac_f32_e32 v146, v124, v150
	v_fmac_f32_e32 v146, v125, v151
	v_add_f32_e32 v164, v152, v146
	v_mul_f32_e32 v146, v115, v149
	v_fmac_f32_e32 v146, v114, v148
	v_fmac_f32_e32 v146, v128, v150
	v_fmac_f32_e32 v146, v129, v151
	v_add_f32_e32 v163, v153, v146
	v_mul_f32_e32 v146, v123, v149
	v_fmac_f32_e32 v146, v122, v148
	v_fmac_f32_e32 v146, v130, v150
	v_fmac_f32_e32 v146, v131, v151
	ds_read2st64_b32 v[148:149], v138 offset0:80 offset1:81
	ds_read2st64_b32 v[150:151], v138 offset0:82 offset1:83
	v_add_f32_e32 v162, v154, v146
	s_waitcnt lgkmcnt(0)
	v_mul_f32_e32 v146, v79, v149
	v_mul_f32_e32 v152, v77, v149
	v_mul_f32_e32 v153, v87, v149
	v_mul_f32_e32 v149, v99, v149
	v_fmac_f32_e32 v149, v98, v148
	v_fmac_f32_e32 v146, v78, v148
	v_fmac_f32_e32 v152, v76, v148
	v_fmac_f32_e32 v153, v86, v148
	s_waitcnt lgkmcnt(0)
	v_fmac_f32_e32 v149, v120, v150
	v_fmac_f32_e32 v146, v112, v150
	v_fmac_f32_e32 v152, v110, v150
	v_fmac_f32_e32 v153, v116, v150
	v_fmac_f32_e32 v149, v121, v151
	v_fmac_f32_e32 v146, v113, v151
	v_fmac_f32_e32 v152, v111, v151
	v_fmac_f32_e32 v153, v117, v151
	v_add_f32_e32 v154, 0, v149
	ds_read2st64_b32 v[148:149], v138 offset0:84 offset1:85
	ds_read2st64_b32 v[150:151], v138 offset0:86 offset1:87
	v_add_f32_e32 v146, 0, v146
	v_add_f32_e32 v152, 0, v152
	v_add_f32_e32 v153, 0, v153
	s_waitcnt lgkmcnt(0)
	v_mul_f32_e32 v155, v71, v149
	v_fmac_f32_e32 v155, v70, v148
	s_waitcnt lgkmcnt(0)
	v_fmac_f32_e32 v155, v104, v150
	v_fmac_f32_e32 v155, v105, v151
	v_add_f32_e32 v146, v146, v155
	v_mul_f32_e32 v155, v75, v149
	v_fmac_f32_e32 v155, v74, v148
	v_fmac_f32_e32 v155, v102, v150
	v_fmac_f32_e32 v155, v103, v151
	v_add_f32_e32 v152, v152, v155
	v_mul_f32_e32 v155, v83, v149
	v_mul_f32_e32 v149, v91, v149
	v_fmac_f32_e32 v149, v90, v148
	v_fmac_f32_e32 v155, v82, v148
	v_fmac_f32_e32 v149, v118, v150
	v_fmac_f32_e32 v155, v106, v150
	v_fmac_f32_e32 v149, v119, v151
	v_fmac_f32_e32 v155, v107, v151
	v_add_f32_e32 v154, v154, v149
	ds_read2st64_b32 v[148:149], v138 offset0:88 offset1:89
	ds_read2st64_b32 v[150:151], v138 offset0:90 offset1:91
	v_add_f32_e32 v153, v153, v155
	s_waitcnt lgkmcnt(0)
	v_mul_f32_e32 v155, v69, v149
	v_fmac_f32_e32 v155, v68, v148
	s_waitcnt lgkmcnt(0)
	v_fmac_f32_e32 v155, v96, v150
	v_fmac_f32_e32 v155, v97, v151
	v_add_f32_e32 v146, v146, v155
	v_mul_f32_e32 v155, v73, v149
	v_fmac_f32_e32 v155, v72, v148
	v_fmac_f32_e32 v155, v92, v150
	v_fmac_f32_e32 v155, v93, v151
	v_add_f32_e32 v152, v152, v155
	v_mul_f32_e32 v155, v81, v149
	v_mul_f32_e32 v149, v89, v149
	v_fmac_f32_e32 v149, v88, v148
	v_fmac_f32_e32 v155, v80, v148
	v_fmac_f32_e32 v149, v108, v150
	v_fmac_f32_e32 v155, v100, v150
	v_fmac_f32_e32 v149, v109, v151
	v_fmac_f32_e32 v155, v101, v151
	v_add_f32_e32 v154, v154, v149
	ds_read2st64_b32 v[148:149], v138 offset0:92 offset1:93
	ds_read2st64_b32 v[150:151], v138 offset0:94 offset1:95
	v_add_f32_e32 v153, v153, v155
	s_waitcnt lgkmcnt(0)
	v_mul_f32_e32 v155, v85, v149
	v_fmac_f32_e32 v155, v84, v148
	s_waitcnt lgkmcnt(0)
	v_fmac_f32_e32 v155, v126, v150
	v_fmac_f32_e32 v155, v127, v151
	v_add_f32_e32 v169, v146, v155
	v_mul_f32_e32 v146, v95, v149
	v_fmac_f32_e32 v146, v94, v148
	v_fmac_f32_e32 v146, v124, v150
	v_fmac_f32_e32 v146, v125, v151
	v_add_f32_e32 v168, v152, v146
	v_mul_f32_e32 v146, v115, v149
	v_fmac_f32_e32 v146, v114, v148
	v_fmac_f32_e32 v146, v128, v150
	v_fmac_f32_e32 v146, v129, v151
	v_add_f32_e32 v167, v153, v146
	v_mul_f32_e32 v146, v123, v149
	v_fmac_f32_e32 v146, v122, v148
	v_fmac_f32_e32 v146, v130, v150
	v_fmac_f32_e32 v146, v131, v151
	ds_read2st64_b32 v[148:149], v138 offset0:96 offset1:97
	ds_read2st64_b32 v[150:151], v138 offset0:98 offset1:99
	v_add_f32_e32 v166, v154, v146
	s_waitcnt lgkmcnt(0)
; #define LAS __attribute__((address_space(3)))
; __device__ __forceinline__ void phase_ma(const Params& p, Frame& F, int l, const bool fd, const float* xin32) {
;     ...
;             for (int ei = 0; ei < 8; ++ei) { const int e = 8 * hh + ei; float a0 = 0.f, a1 = 0.f, a2 = 0.f, a3 = 0.f;
; #pragma unroll
;                 for (int j = 0; j < 4; ++j) { const LAS float* w = wrp + (((e * 4 + j) * 4) << 6) + F.lane; const float w0 = w[0], w1 = w[64], w2 = w[128], w3 = w[192];
;                     a0 += h[0][j].x * w0 + h[0][j].y * w1 + h[0][j].z * w2 + h[0][j].w * w3; a1 += h[1][j].x * w0 + h[1][j].y * w1 + h[1][j].z * w2 + h[1][j].w * w3;
;                     a2 += h[2][j].x * w0 + h[2][j].y * w1 + h[2][j].z * w2 + h[2][j].w * w3; a3 += h[3][j].x * w0 + h[3][j].y * w1 + h[3][j].z * w2 + h[3][j].w * w3; }
;                 v[0][ei] = a0; v[1][ei] = a1; v[2][ei] = a2; v[3][ei] = a3; }
	v_mul_f32_e32 v146, v79, v149
	v_mul_f32_e32 v152, v77, v149
	v_mul_f32_e32 v153, v87, v149
	v_mul_f32_e32 v149, v99, v149
	v_fmac_f32_e32 v149, v98, v148
	v_fmac_f32_e32 v146, v78, v148
	v_fmac_f32_e32 v152, v76, v148
	v_fmac_f32_e32 v153, v86, v148
	s_waitcnt lgkmcnt(0)
	v_fmac_f32_e32 v149, v120, v150
	v_fmac_f32_e32 v146, v112, v150
	v_fmac_f32_e32 v152, v110, v150
	v_fmac_f32_e32 v153, v116, v150
	v_fmac_f32_e32 v149, v121, v151
	v_fmac_f32_e32 v146, v113, v151
	v_fmac_f32_e32 v152, v111, v151
	v_fmac_f32_e32 v153, v117, v151
	v_add_f32_e32 v154, 0, v149
	ds_read2st64_b32 v[148:149], v138 offset0:100 offset1:101
	ds_read2st64_b32 v[150:151], v138 offset0:102 offset1:103
	v_add_f32_e32 v146, 0, v146
	v_add_f32_e32 v152, 0, v152
	v_add_f32_e32 v153, 0, v153
	s_waitcnt lgkmcnt(0)
	v_mul_f32_e32 v155, v71, v149
	v_fmac_f32_e32 v155, v70, v148
	s_waitcnt lgkmcnt(0)
	v_fmac_f32_e32 v155, v104, v150
	v_fmac_f32_e32 v155, v105, v151
	v_add_f32_e32 v146, v146, v155
	v_mul_f32_e32 v155, v75, v149
	v_fmac_f32_e32 v155, v74, v148
	v_fmac_f32_e32 v155, v102, v150
	v_fmac_f32_e32 v155, v103, v151
	v_add_f32_e32 v152, v152, v155
	v_mul_f32_e32 v155, v83, v149
	v_mul_f32_e32 v149, v91, v149
	v_fmac_f32_e32 v149, v90, v148
	v_fmac_f32_e32 v155, v82, v148
	v_fmac_f32_e32 v149, v118, v150
	v_fmac_f32_e32 v155, v106, v150
	v_fmac_f32_e32 v149, v119, v151
	v_fmac_f32_e32 v155, v107, v151
	v_add_f32_e32 v154, v154, v149
	ds_read2st64_b32 v[148:149], v138 offset0:104 offset1:105
	ds_read2st64_b32 v[150:151], v138 offset0:106 offset1:107
	v_add_f32_e32 v153, v153, v155
	s_waitcnt lgkmcnt(0)
	v_mul_f32_e32 v155, v69, v149
	v_fmac_f32_e32 v155, v68, v148
	s_waitcnt lgkmcnt(0)
	v_fmac_f32_e32 v155, v96, v150
	v_fmac_f32_e32 v155, v97, v151
	v_add_f32_e32 v146, v146, v155
	v_mul_f32_e32 v155, v73, v149
	v_fmac_f32_e32 v155, v72, v148
	v_fmac_f32_e32 v155, v92, v150
	v_fmac_f32_e32 v155, v93, v151
	v_add_f32_e32 v152, v152, v155
	v_mul_f32_e32 v155, v81, v149
	v_mul_f32_e32 v149, v89, v149
	v_fmac_f32_e32 v149, v88, v148
	v_fmac_f32_e32 v155, v80, v148
	v_fmac_f32_e32 v149, v108, v150
	v_fmac_f32_e32 v155, v100, v150
	v_fmac_f32_e32 v149, v109, v151
	v_fmac_f32_e32 v155, v101, v151
	v_add_f32_e32 v154, v154, v149
	ds_read2st64_b32 v[148:149], v138 offset0:108 offset1:109
	ds_read2st64_b32 v[150:151], v138 offset0:110 offset1:111
	v_add_f32_e32 v153, v153, v155
	s_waitcnt lgkmcnt(0)
	v_mul_f32_e32 v155, v85, v149
	v_fmac_f32_e32 v155, v84, v148
	s_waitcnt lgkmcnt(0)
	v_fmac_f32_e32 v155, v126, v150
	v_fmac_f32_e32 v155, v127, v151
	v_add_f32_e32 v146, v146, v155
	v_mul_f32_e32 v155, v95, v149
	v_fmac_f32_e32 v155, v94, v148
	v_fmac_f32_e32 v155, v124, v150
	v_fmac_f32_e32 v155, v125, v151
	v_add_f32_e32 v172, v152, v155
	v_mul_f32_e32 v152, v115, v149
	v_mul_f32_e32 v149, v123, v149
	v_fmac_f32_e32 v149, v122, v148
	v_fmac_f32_e32 v152, v114, v148
	v_fmac_f32_e32 v149, v130, v150
	v_fmac_f32_e32 v152, v128, v150
	v_fmac_f32_e32 v149, v131, v151
	v_fmac_f32_e32 v152, v129, v151
	v_add_f32_e32 v170, v154, v149
	ds_read2st64_b32 v[148:149], v138 offset0:112 offset1:113
	ds_read2st64_b32 v[150:151], v138 offset0:114 offset1:115
	v_add_f32_e32 v171, v153, v152
	s_waitcnt lgkmcnt(0)
	v_mul_f32_e32 v152, v79, v149
	v_mul_f32_e32 v153, v77, v149
	v_mul_f32_e32 v154, v87, v149
	v_mul_f32_e32 v149, v99, v149
	v_fmac_f32_e32 v149, v98, v148
	v_fmac_f32_e32 v152, v78, v148
	v_fmac_f32_e32 v153, v76, v148
	v_fmac_f32_e32 v154, v86, v148
	s_waitcnt lgkmcnt(0)
	v_fmac_f32_e32 v149, v120, v150
	v_fmac_f32_e32 v152, v112, v150
	v_fmac_f32_e32 v153, v110, v150
	v_fmac_f32_e32 v154, v116, v150
	v_fmac_f32_e32 v149, v121, v151
	v_fmac_f32_e32 v152, v113, v151
	v_fmac_f32_e32 v153, v111, v151
	v_fmac_f32_e32 v154, v117, v151
	v_add_f32_e32 v155, 0, v149
	ds_read2st64_b32 v[148:149], v138 offset0:116 offset1:117
	ds_read2st64_b32 v[150:151], v138 offset0:118 offset1:119
	v_add_f32_e32 v152, 0, v152
	v_add_f32_e32 v153, 0, v153
	v_add_f32_e32 v154, 0, v154
	s_waitcnt lgkmcnt(0)
	v_mul_f32_e32 v158, v71, v149
	v_fmac_f32_e32 v158, v70, v148
	s_waitcnt lgkmcnt(0)
	v_fmac_f32_e32 v158, v104, v150
	v_fmac_f32_e32 v158, v105, v151
	v_add_f32_e32 v152, v152, v158
	v_mul_f32_e32 v158, v75, v149
	v_fmac_f32_e32 v158, v74, v148
	v_fmac_f32_e32 v158, v102, v150
	v_fmac_f32_e32 v158, v103, v151
	v_add_f32_e32 v153, v153, v158
	v_mul_f32_e32 v158, v83, v149
	v_mul_f32_e32 v149, v91, v149
	v_fmac_f32_e32 v149, v90, v148
	v_fmac_f32_e32 v158, v82, v148
	v_fmac_f32_e32 v149, v118, v150
	v_fmac_f32_e32 v158, v106, v150
	v_fmac_f32_e32 v149, v119, v151
	v_fmac_f32_e32 v158, v107, v151
	v_add_f32_e32 v155, v155, v149
	ds_read2st64_b32 v[148:149], v138 offset0:120 offset1:121
	ds_read2st64_b32 v[150:151], v138 offset0:122 offset1:123
	v_add_f32_e32 v154, v154, v158
	s_waitcnt lgkmcnt(0)
	v_mul_f32_e32 v158, v69, v149
	v_fmac_f32_e32 v158, v68, v148
	s_waitcnt lgkmcnt(0)
	v_fmac_f32_e32 v158, v96, v150
	v_fmac_f32_e32 v158, v97, v151
	v_add_f32_e32 v152, v152, v158
	v_mul_f32_e32 v158, v73, v149
	v_fmac_f32_e32 v158, v72, v148
	v_fmac_f32_e32 v158, v92, v150
	v_fmac_f32_e32 v158, v93, v151
	v_add_f32_e32 v153, v153, v158
	v_mul_f32_e32 v158, v81, v149
	v_mul_f32_e32 v149, v89, v149
	v_fmac_f32_e32 v149, v88, v148
	v_fmac_f32_e32 v158, v80, v148
	v_fmac_f32_e32 v149, v108, v150
	v_fmac_f32_e32 v158, v100, v150
	v_fmac_f32_e32 v149, v109, v151
	v_fmac_f32_e32 v158, v101, v151
	v_add_f32_e32 v155, v155, v149
	ds_read2st64_b32 v[148:149], v138 offset0:124 offset1:125
	ds_read2st64_b32 v[150:151], v138 offset0:126 offset1:127
	v_add_f32_e32 v154, v154, v158
	s_waitcnt lgkmcnt(0)
; #define LAS __attribute__((address_space(3)))
; __device__ __forceinline__ float shx(float v, int o, int lane) { return __builtin_bit_cast(float, __builtin_amdgcn_ds_bpermute((lane ^ o) << 2, __builtin_bit_cast(int, v))); }
; __device__ __forceinline__ void phase_ma(const Params& p, Frame& F, int l, const bool fd, const float* xin32) {
;     ...
;             for (int ei = 0; ei < 8; ++ei) { const int e = 8 * hh + ei; float a0 = 0.f, a1 = 0.f, a2 = 0.f, a3 = 0.f;
; #pragma unroll
;                 for (int j = 0; j < 4; ++j) { const LAS float* w = wrp + (((e * 4 + j) * 4) << 6) + F.lane; const float w0 = w[0], w1 = w[64], w2 = w[128], w3 = w[192];
;                     a0 += h[0][j].x * w0 + h[0][j].y * w1 + h[0][j].z * w2 + h[0][j].w * w3; a1 += h[1][j].x * w0 + h[1][j].y * w1 + h[1][j].z * w2 + h[1][j].w * w3;
;                     a2 += h[2][j].x * w0 + h[2][j].y * w1 + h[2][j].z * w2 + h[2][j].w * w3; a3 += h[3][j].x * w0 + h[3][j].y * w1 + h[3][j].z * w2 + h[3][j].w * w3; }
;                 v[0][ei] = a0; v[1][ei] = a1; v[2][ei] = a2; v[3][ei] = a3; }
;     ...
;             for (int r = 0; r < 4; ++r) { float t4[4], t2[2];
;                 { const bool hi = (F.lane & 32) != 0;
; #pragma unroll
;                   for (int i = 0; i < 4; ++i) { const float send = hi ? v[r][i] : v[r][i + 4], keep = hi ? v[r][i + 4] : v[r][i]; t4[i] = keep + shx(send, 32, F.lane); } }
;                 { const bool hi = (F.lane & 16) != 0;
; #pragma unroll
;                   for (int i = 0; i < 2; ++i) { const float send = hi ? t4[i] : t4[i + 2], keep = hi ? t4[i + 2] : t4[i]; t2[i] = keep + shx(send, 16, F.lane); } }
;                 { const bool hi = (F.lane & 8) != 0; const float send = hi ? t2[0] : t2[1], keep = hi ? t2[1] : t2[0]; th2[r][hh] = keep + shx(send, 8, F.lane); } }
	v_mul_f32_e32 v158, v85, v149
	v_fmac_f32_e32 v158, v84, v148
	s_waitcnt lgkmcnt(0)
	v_fmac_f32_e32 v158, v126, v150
	v_fmac_f32_e32 v158, v127, v151
	v_add_f32_e32 v152, v152, v158
	v_mul_f32_e32 v158, v95, v149
	v_fmac_f32_e32 v158, v94, v148
	v_fmac_f32_e32 v158, v124, v150
	v_fmac_f32_e32 v158, v125, v151
	v_add_f32_e32 v153, v153, v158
	v_mul_f32_e32 v158, v115, v149
	v_mul_f32_e32 v149, v123, v149
	v_fmac_f32_e32 v149, v122, v148
	v_fmac_f32_e32 v149, v130, v150
	v_fmac_f32_e32 v149, v131, v151
	v_fmac_f32_e32 v158, v114, v148
	v_add_f32_e32 v148, v155, v149
	v_permlane32_swap_b32 v33, v165
	v_add_f32_e32 v33, v33, v165
	v_fmac_f32_e32 v158, v128, v150
	v_fmac_f32_e32 v158, v129, v151
	v_add_f32_e32 v154, v154, v158
	s_waitcnt lgkmcnt(0)
	v_permlane32_swap_b32 v37, v169
	v_add_f32_e32 v37, v37, v169
	s_waitcnt lgkmcnt(0)
	v_permlane32_swap_b32 v140, v146
	v_add_f32_e32 v140, v140, v146
	s_waitcnt lgkmcnt(0)
	v_permlane32_swap_b32 v156, v152
	v_add_f32_e32 v146, v156, v152
	s_waitcnt lgkmcnt(0)
	v_permlane16_swap_b32 v33, v140
	v_add_f32_e32 v33, v33, v140
	s_waitcnt lgkmcnt(0)
	v_permlane16_swap_b32 v37, v146
	v_add_f32_e32 v37, v37, v146
	s_waitcnt lgkmcnt(0)
	v_cndmask_b32_e64 v140, v33, v37, s[42:43]
	v_cndmask_b32_e64 v33, v37, v33, s[42:43]
	s_nop 0
	v_mov_b32_dpp v37, v140 row_ror:8 row_mask:0xf bank_mask:0xf
	s_waitcnt lgkmcnt(0)
	v_add_f32_e32 v140, v33, v37
	s_nop 2
	v_permlane32_swap_b32 v32, v164
	v_add_f32_e32 v32, v32, v164
	s_waitcnt lgkmcnt(0)
	v_permlane32_swap_b32 v34, v168
	v_add_f32_e32 v33, v34, v168
	s_waitcnt lgkmcnt(0)
	v_permlane32_swap_b32 v142, v172
	v_add_f32_e32 v34, v142, v172
	s_waitcnt lgkmcnt(0)
	v_permlane32_swap_b32 v147, v153
	v_add_f32_e32 v37, v147, v153
	s_waitcnt lgkmcnt(0)
	v_permlane16_swap_b32 v32, v34
	v_add_f32_e32 v32, v32, v34
	s_waitcnt lgkmcnt(0)
	v_permlane32_swap_b32 v35, v163
	v_add_f32_e32 v35, v35, v163
	v_permlane16_swap_b32 v33, v37
	v_add_f32_e32 v33, v33, v37
	s_waitcnt lgkmcnt(0)
	v_permlane32_swap_b32 v36, v167
	v_add_f32_e32 v36, v36, v167
	s_waitcnt lgkmcnt(0)
	v_cndmask_b32_e64 v34, v32, v33, s[42:43]
	s_nop 1
	v_mov_b32_dpp v34, v34 row_ror:8 row_mask:0xf bank_mask:0xf
	s_waitcnt lgkmcnt(0)
	s_nop 3
	v_permlane32_swap_b32 v141, v171
	v_add_f32_e32 v37, v141, v171
	s_waitcnt lgkmcnt(0)
	v_permlane32_swap_b32 v144, v154
	v_add_f32_e32 v141, v144, v154
	s_waitcnt lgkmcnt(0)
	v_permlane16_swap_b32 v35, v37
	v_add_f32_e32 v35, v35, v37
	s_waitcnt lgkmcnt(0)
	v_permlane32_swap_b32 v38, v162
	v_add_f32_e32 v38, v38, v162
	v_permlane16_swap_b32 v36, v141
	v_add_f32_e32 v36, v36, v141
	s_waitcnt lgkmcnt(0)
	v_permlane32_swap_b32 v39, v166
	v_add_f32_e32 v39, v39, v166
	s_waitcnt lgkmcnt(0)
	v_cndmask_b32_e64 v37, v35, v36, s[42:43]
	s_nop 1
	v_mov_b32_dpp v37, v37 row_ror:8 row_mask:0xf bank_mask:0xf
	s_waitcnt lgkmcnt(0)
	s_nop 3
	v_permlane32_swap_b32 v139, v170
	v_add_f32_e32 v139, v139, v170
	s_waitcnt lgkmcnt(0)
	v_permlane32_swap_b32 v143, v148
	v_add_f32_e32 v141, v143, v148
	s_waitcnt lgkmcnt(0)
	v_permlane16_swap_b32 v38, v139
	v_add_f32_e32 v38, v38, v139
	ds_read2st64_b32 v[142:143], v138 offset0:128 offset1:129
	ds_read2st64_b32 v[146:147], v138 offset0:130 offset1:131
	s_waitcnt lgkmcnt(0)
	v_cndmask_b32_e64 v139, v39, v141, s[40:41]
	v_cndmask_b32_e64 v39, v141, v39, s[40:41]
	s_waitcnt lgkmcnt(1)
	v_mul_f32_e32 v141, v79, v143
	v_mul_f32_e32 v144, v77, v143
	v_mul_f32_e32 v148, v87, v143
	v_mul_f32_e32 v143, v99, v143
	v_fmac_f32_e32 v143, v98, v142
	v_fmac_f32_e32 v141, v78, v142
	v_fmac_f32_e32 v144, v76, v142
	v_fmac_f32_e32 v148, v86, v142
	s_waitcnt lgkmcnt(0)
	v_fmac_f32_e32 v143, v120, v146
	v_fmac_f32_e32 v141, v112, v146
	v_fmac_f32_e32 v144, v110, v146
	v_fmac_f32_e32 v148, v116, v146
	v_fmac_f32_e32 v143, v121, v147
	v_fmac_f32_e32 v141, v113, v147
	v_fmac_f32_e32 v144, v111, v147
	v_fmac_f32_e32 v148, v117, v147
	v_add_f32_e32 v149, 0, v143
	ds_read2st64_b32 v[142:143], v138 offset0:132 offset1:133
	ds_read2st64_b32 v[146:147], v138 offset0:134 offset1:135
	v_add_f32_e32 v141, 0, v141
	v_add_f32_e32 v144, 0, v144
	v_add_f32_e32 v148, 0, v148
	s_waitcnt lgkmcnt(0)
	v_mul_f32_e32 v150, v71, v143
	v_fmac_f32_e32 v150, v70, v142
	s_waitcnt lgkmcnt(0)
	v_fmac_f32_e32 v150, v104, v146
	v_fmac_f32_e32 v150, v105, v147
	v_add_f32_e32 v141, v141, v150
	v_mul_f32_e32 v150, v75, v143
	v_fmac_f32_e32 v150, v74, v142
	v_fmac_f32_e32 v150, v102, v146
	v_fmac_f32_e32 v150, v103, v147
	v_add_f32_e32 v144, v144, v150
	v_mul_f32_e32 v150, v83, v143
	v_mul_f32_e32 v143, v91, v143
	v_fmac_f32_e32 v143, v90, v142
	v_fmac_f32_e32 v150, v82, v142
	v_fmac_f32_e32 v143, v118, v146
	v_fmac_f32_e32 v150, v106, v146
	v_fmac_f32_e32 v143, v119, v147
	v_fmac_f32_e32 v150, v107, v147
	v_add_f32_e32 v149, v149, v143
	ds_read2st64_b32 v[142:143], v138 offset0:136 offset1:137
	ds_read2st64_b32 v[146:147], v138 offset0:138 offset1:139
	v_add_f32_e32 v148, v148, v150
	v_mov_b32_e32 v139, v139
	v_mov_b32_e32 v190, v139
	s_nop 1
	v_permlane16_swap_b32 v139, v190
	v_cndmask_b32_e64 v139, v139, v190, s[40:41]
	s_waitcnt lgkmcnt(0)
	v_mul_f32_e32 v150, v69, v143
	v_fmac_f32_e32 v150, v68, v142
	s_waitcnt lgkmcnt(0)
	v_fmac_f32_e32 v150, v96, v146
	v_fmac_f32_e32 v150, v97, v147
	v_add_f32_e32 v141, v141, v150
	v_mul_f32_e32 v150, v73, v143
	v_fmac_f32_e32 v150, v72, v142
	v_fmac_f32_e32 v150, v92, v146
	v_fmac_f32_e32 v150, v93, v147
	v_add_f32_e32 v150, v144, v150
	v_mul_f32_e32 v144, v81, v143
	v_mul_f32_e32 v143, v89, v143
	v_fmac_f32_e32 v144, v80, v142
	v_fmac_f32_e32 v143, v88, v142
	v_fmac_f32_e32 v144, v100, v146
	v_fmac_f32_e32 v143, v108, v146
	v_fmac_f32_e32 v144, v101, v147
	v_fmac_f32_e32 v143, v109, v147
	v_add_f32_e32 v151, v148, v144
	v_add_f32_e32 v152, v149, v143
	ds_read2st64_b32 v[146:147], v138 offset0:140 offset1:141
	ds_read2st64_b32 v[148:149], v138 offset0:142 offset1:143
	s_waitcnt lgkmcnt(2)
; #define LAS __attribute__((address_space(3)))
; __device__ __forceinline__ float shx(float v, int o, int lane) { return __builtin_bit_cast(float, __builtin_amdgcn_ds_bpermute((lane ^ o) << 2, __builtin_bit_cast(int, v))); }
; __device__ __forceinline__ void phase_ma(const Params& p, Frame& F, int l, const bool fd, const float* xin32) {
;     ...
;             for (int ei = 0; ei < 8; ++ei) { const int e = 8 * hh + ei; float a0 = 0.f, a1 = 0.f, a2 = 0.f, a3 = 0.f;
; #pragma unroll
;                 for (int j = 0; j < 4; ++j) { const LAS float* w = wrp + (((e * 4 + j) * 4) << 6) + F.lane; const float w0 = w[0], w1 = w[64], w2 = w[128], w3 = w[192];
;                     a0 += h[0][j].x * w0 + h[0][j].y * w1 + h[0][j].z * w2 + h[0][j].w * w3; a1 += h[1][j].x * w0 + h[1][j].y * w1 + h[1][j].z * w2 + h[1][j].w * w3;
;                     a2 += h[2][j].x * w0 + h[2][j].y * w1 + h[2][j].z * w2 + h[2][j].w * w3; a3 += h[3][j].x * w0 + h[3][j].y * w1 + h[3][j].z * w2 + h[3][j].w * w3; }
;                 v[0][ei] = a0; v[1][ei] = a1; v[2][ei] = a2; v[3][ei] = a3; }
;     ...
;                 { const bool hi = (F.lane & 8) != 0; const float send = hi ? t2[0] : t2[1], keep = hi ? t2[1] : t2[0]; th2[r][hh] = keep + shx(send, 8, F.lane); } }
	v_add_f32_e32 v39, v39, v139
	v_cndmask_b32_e64 v139, v38, v39, s[42:43]
	s_nop 1
	v_mov_b32_dpp v139, v139 row_ror:8 row_mask:0xf bank_mask:0xf
	s_waitcnt lgkmcnt(0)
	v_mul_f32_e32 v142, v85, v147
	v_fmac_f32_e32 v142, v84, v146
	s_waitcnt lgkmcnt(0)
	v_fmac_f32_e32 v142, v126, v148
	v_fmac_f32_e32 v142, v127, v149
	v_add_f32_e32 v144, v141, v142
	v_mul_f32_e32 v141, v95, v147
	v_fmac_f32_e32 v141, v94, v146
	v_fmac_f32_e32 v141, v124, v148
	v_fmac_f32_e32 v141, v125, v149
	v_add_f32_e32 v143, v150, v141
	v_mul_f32_e32 v141, v115, v147
	v_fmac_f32_e32 v141, v114, v146
	v_fmac_f32_e32 v141, v128, v148
	v_fmac_f32_e32 v141, v129, v149
	v_add_f32_e32 v142, v151, v141
	v_mul_f32_e32 v141, v123, v147
	v_fmac_f32_e32 v141, v122, v146
	v_fmac_f32_e32 v141, v130, v148
	v_fmac_f32_e32 v141, v131, v149
	ds_read2st64_b32 v[146:147], v138 offset0:144 offset1:145
	ds_read2st64_b32 v[148:149], v138 offset0:146 offset1:147
	v_add_f32_e32 v141, v152, v141
	s_waitcnt lgkmcnt(0)
	v_mul_f32_e32 v150, v79, v147
	v_mul_f32_e32 v151, v77, v147
	v_mul_f32_e32 v152, v87, v147
	v_mul_f32_e32 v147, v99, v147
	v_fmac_f32_e32 v147, v98, v146
	v_fmac_f32_e32 v150, v78, v146
	v_fmac_f32_e32 v151, v76, v146
	v_fmac_f32_e32 v152, v86, v146
	s_waitcnt lgkmcnt(0)
	v_fmac_f32_e32 v147, v120, v148
	v_fmac_f32_e32 v150, v112, v148
	v_fmac_f32_e32 v151, v110, v148
	v_fmac_f32_e32 v152, v116, v148
	v_fmac_f32_e32 v147, v121, v149
	v_fmac_f32_e32 v150, v113, v149
	v_fmac_f32_e32 v151, v111, v149
	v_fmac_f32_e32 v152, v117, v149
	v_add_f32_e32 v153, 0, v147
	ds_read2st64_b32 v[146:147], v138 offset0:148 offset1:149
	ds_read2st64_b32 v[148:149], v138 offset0:150 offset1:151
	v_add_f32_e32 v150, 0, v150
	v_add_f32_e32 v151, 0, v151
	v_add_f32_e32 v152, 0, v152
	s_waitcnt lgkmcnt(0)
	v_mul_f32_e32 v154, v71, v147
	v_fmac_f32_e32 v154, v70, v146
	s_waitcnt lgkmcnt(0)
	v_fmac_f32_e32 v154, v104, v148
	v_fmac_f32_e32 v154, v105, v149
	v_add_f32_e32 v150, v150, v154
	v_mul_f32_e32 v154, v75, v147
	v_fmac_f32_e32 v154, v74, v146
	v_fmac_f32_e32 v154, v102, v148
	v_fmac_f32_e32 v154, v103, v149
	v_add_f32_e32 v151, v151, v154
	v_mul_f32_e32 v154, v83, v147
	v_mul_f32_e32 v147, v91, v147
	v_fmac_f32_e32 v147, v90, v146
	v_fmac_f32_e32 v154, v82, v146
	v_fmac_f32_e32 v147, v118, v148
	v_fmac_f32_e32 v154, v106, v148
	v_fmac_f32_e32 v147, v119, v149
	v_fmac_f32_e32 v154, v107, v149
	v_add_f32_e32 v153, v153, v147
	ds_read2st64_b32 v[146:147], v138 offset0:152 offset1:153
	ds_read2st64_b32 v[148:149], v138 offset0:154 offset1:155
	v_add_f32_e32 v152, v152, v154
	s_waitcnt lgkmcnt(0)
	v_mul_f32_e32 v154, v69, v147
	v_fmac_f32_e32 v154, v68, v146
	s_waitcnt lgkmcnt(0)
	v_fmac_f32_e32 v154, v96, v148
	v_fmac_f32_e32 v154, v97, v149
	v_add_f32_e32 v150, v150, v154
	v_mul_f32_e32 v154, v73, v147
	v_fmac_f32_e32 v154, v72, v146
	v_fmac_f32_e32 v154, v92, v148
	v_fmac_f32_e32 v154, v93, v149
	v_add_f32_e32 v151, v151, v154
	v_mul_f32_e32 v154, v81, v147
	v_mul_f32_e32 v147, v89, v147
	v_fmac_f32_e32 v147, v88, v146
	v_fmac_f32_e32 v154, v80, v146
	v_fmac_f32_e32 v147, v108, v148
	v_fmac_f32_e32 v154, v100, v148
	v_fmac_f32_e32 v147, v109, v149
	v_fmac_f32_e32 v154, v101, v149
	v_add_f32_e32 v153, v153, v147
	ds_read2st64_b32 v[146:147], v138 offset0:156 offset1:157
	ds_read2st64_b32 v[148:149], v138 offset0:158 offset1:159
	v_add_f32_e32 v152, v152, v154
	s_waitcnt lgkmcnt(0)
	v_mul_f32_e32 v154, v85, v147
	v_fmac_f32_e32 v154, v84, v146
	s_waitcnt lgkmcnt(0)
	v_fmac_f32_e32 v154, v126, v148
	v_fmac_f32_e32 v154, v127, v149
	v_add_f32_e32 v163, v150, v154
	v_mul_f32_e32 v150, v95, v147
	v_fmac_f32_e32 v150, v94, v146
	v_fmac_f32_e32 v150, v124, v148
	v_fmac_f32_e32 v150, v125, v149
	v_add_f32_e32 v162, v151, v150
	v_mul_f32_e32 v150, v115, v147
	v_fmac_f32_e32 v150, v114, v146
	v_mul_f32_e32 v147, v123, v147
	v_fmac_f32_e32 v150, v128, v148
	v_fmac_f32_e32 v147, v122, v146
	v_fmac_f32_e32 v150, v129, v149
	v_fmac_f32_e32 v147, v130, v148
	v_add_f32_e32 v156, v152, v150
	v_fmac_f32_e32 v147, v131, v149
	ds_read2st64_b32 v[148:149], v138 offset0:160 offset1:161
	ds_read2st64_b32 v[150:151], v138 offset0:162 offset1:163
	v_add_f32_e32 v147, v153, v147
	s_waitcnt lgkmcnt(0)
	v_mul_f32_e32 v146, v79, v149
	v_mul_f32_e32 v152, v77, v149
	v_mul_f32_e32 v153, v87, v149
	v_mul_f32_e32 v149, v99, v149
	v_fmac_f32_e32 v149, v98, v148
	v_fmac_f32_e32 v146, v78, v148
	v_fmac_f32_e32 v152, v76, v148
	v_fmac_f32_e32 v153, v86, v148
	s_waitcnt lgkmcnt(0)
	v_fmac_f32_e32 v149, v120, v150
	v_fmac_f32_e32 v146, v112, v150
	v_fmac_f32_e32 v152, v110, v150
	v_fmac_f32_e32 v153, v116, v150
	v_fmac_f32_e32 v149, v121, v151
	v_fmac_f32_e32 v146, v113, v151
	v_fmac_f32_e32 v152, v111, v151
	v_fmac_f32_e32 v153, v117, v151
	v_add_f32_e32 v154, 0, v149
	ds_read2st64_b32 v[148:149], v138 offset0:164 offset1:165
	ds_read2st64_b32 v[150:151], v138 offset0:166 offset1:167
	v_add_f32_e32 v146, 0, v146
	v_add_f32_e32 v152, 0, v152
	v_add_f32_e32 v153, 0, v153
	s_waitcnt lgkmcnt(0)
	v_mul_f32_e32 v155, v71, v149
	v_fmac_f32_e32 v155, v70, v148
	s_waitcnt lgkmcnt(0)
	v_fmac_f32_e32 v155, v104, v150
	v_fmac_f32_e32 v155, v105, v151
	v_add_f32_e32 v146, v146, v155
	v_mul_f32_e32 v155, v75, v149
	v_fmac_f32_e32 v155, v74, v148
	v_fmac_f32_e32 v155, v102, v150
	v_fmac_f32_e32 v155, v103, v151
	v_add_f32_e32 v152, v152, v155
	v_mul_f32_e32 v155, v83, v149
	v_mul_f32_e32 v149, v91, v149
	v_fmac_f32_e32 v149, v90, v148
	v_fmac_f32_e32 v155, v82, v148
	v_fmac_f32_e32 v149, v118, v150
	v_fmac_f32_e32 v155, v106, v150
	v_fmac_f32_e32 v149, v119, v151
	v_fmac_f32_e32 v155, v107, v151
	v_add_f32_e32 v154, v154, v149
	ds_read2st64_b32 v[148:149], v138 offset0:168 offset1:169
	ds_read2st64_b32 v[150:151], v138 offset0:170 offset1:171
	v_add_f32_e32 v153, v153, v155
	s_waitcnt lgkmcnt(0)
; #define LAS __attribute__((address_space(3)))
; __device__ __forceinline__ void phase_ma(const Params& p, Frame& F, int l, const bool fd, const float* xin32) {
;     ...
;             for (int ei = 0; ei < 8; ++ei) { const int e = 8 * hh + ei; float a0 = 0.f, a1 = 0.f, a2 = 0.f, a3 = 0.f;
; #pragma unroll
;                 for (int j = 0; j < 4; ++j) { const LAS float* w = wrp + (((e * 4 + j) * 4) << 6) + F.lane; const float w0 = w[0], w1 = w[64], w2 = w[128], w3 = w[192];
;                     a0 += h[0][j].x * w0 + h[0][j].y * w1 + h[0][j].z * w2 + h[0][j].w * w3; a1 += h[1][j].x * w0 + h[1][j].y * w1 + h[1][j].z * w2 + h[1][j].w * w3;
;                     a2 += h[2][j].x * w0 + h[2][j].y * w1 + h[2][j].z * w2 + h[2][j].w * w3; a3 += h[3][j].x * w0 + h[3][j].y * w1 + h[3][j].z * w2 + h[3][j].w * w3; }
;                 v[0][ei] = a0; v[1][ei] = a1; v[2][ei] = a2; v[3][ei] = a3; }
	v_mul_f32_e32 v155, v69, v149
	v_fmac_f32_e32 v155, v68, v148
	s_waitcnt lgkmcnt(0)
	v_fmac_f32_e32 v155, v96, v150
	v_fmac_f32_e32 v155, v97, v151
	v_add_f32_e32 v146, v146, v155
	v_mul_f32_e32 v155, v73, v149
	v_fmac_f32_e32 v155, v72, v148
	v_fmac_f32_e32 v155, v92, v150
	v_fmac_f32_e32 v155, v93, v151
	v_add_f32_e32 v152, v152, v155
	v_mul_f32_e32 v155, v81, v149
	v_mul_f32_e32 v149, v89, v149
	v_fmac_f32_e32 v149, v88, v148
	v_fmac_f32_e32 v155, v80, v148
	v_fmac_f32_e32 v149, v108, v150
	v_fmac_f32_e32 v155, v100, v150
	v_fmac_f32_e32 v149, v109, v151
	v_fmac_f32_e32 v155, v101, v151
	v_add_f32_e32 v154, v154, v149
	ds_read2st64_b32 v[148:149], v138 offset0:172 offset1:173
	ds_read2st64_b32 v[150:151], v138 offset0:174 offset1:175
	v_add_f32_e32 v153, v153, v155
	s_waitcnt lgkmcnt(0)
	v_mul_f32_e32 v155, v85, v149
	v_fmac_f32_e32 v155, v84, v148
	s_waitcnt lgkmcnt(0)
	v_fmac_f32_e32 v155, v126, v150
	v_fmac_f32_e32 v155, v127, v151
	v_add_f32_e32 v167, v146, v155
	v_mul_f32_e32 v146, v95, v149
	v_fmac_f32_e32 v146, v94, v148
	v_fmac_f32_e32 v146, v124, v150
	v_fmac_f32_e32 v146, v125, v151
	v_add_f32_e32 v166, v152, v146
	v_mul_f32_e32 v146, v115, v149
	v_fmac_f32_e32 v146, v114, v148
	v_fmac_f32_e32 v146, v128, v150
	v_fmac_f32_e32 v146, v129, v151
	v_add_f32_e32 v165, v153, v146
	v_mul_f32_e32 v146, v123, v149
	v_fmac_f32_e32 v146, v122, v148
	v_fmac_f32_e32 v146, v130, v150
	v_fmac_f32_e32 v146, v131, v151
	ds_read2st64_b32 v[148:149], v138 offset0:176 offset1:177
	ds_read2st64_b32 v[150:151], v138 offset0:178 offset1:179
	v_add_f32_e32 v164, v154, v146
	s_waitcnt lgkmcnt(0)
	v_mul_f32_e32 v146, v79, v149
	v_mul_f32_e32 v152, v77, v149
	v_mul_f32_e32 v153, v87, v149
	v_mul_f32_e32 v149, v99, v149
	v_fmac_f32_e32 v149, v98, v148
	v_fmac_f32_e32 v146, v78, v148
	v_fmac_f32_e32 v152, v76, v148
	v_fmac_f32_e32 v153, v86, v148
	s_waitcnt lgkmcnt(0)
	v_fmac_f32_e32 v149, v120, v150
	v_fmac_f32_e32 v146, v112, v150
	v_fmac_f32_e32 v152, v110, v150
	v_fmac_f32_e32 v153, v116, v150
	v_fmac_f32_e32 v149, v121, v151
	v_fmac_f32_e32 v146, v113, v151
	v_fmac_f32_e32 v152, v111, v151
	v_fmac_f32_e32 v153, v117, v151
	v_add_f32_e32 v154, 0, v149
	ds_read2st64_b32 v[148:149], v138 offset0:180 offset1:181
	ds_read2st64_b32 v[150:151], v138 offset0:182 offset1:183
	v_add_f32_e32 v146, 0, v146
	v_add_f32_e32 v152, 0, v152
	v_add_f32_e32 v153, 0, v153
	s_waitcnt lgkmcnt(0)
	v_mul_f32_e32 v155, v71, v149
	v_fmac_f32_e32 v155, v70, v148
	s_waitcnt lgkmcnt(0)
	v_fmac_f32_e32 v155, v104, v150
	v_fmac_f32_e32 v155, v105, v151
	v_add_f32_e32 v146, v146, v155
	v_mul_f32_e32 v155, v75, v149
	v_fmac_f32_e32 v155, v74, v148
	v_fmac_f32_e32 v155, v102, v150
	v_fmac_f32_e32 v155, v103, v151
	v_add_f32_e32 v152, v152, v155
	v_mul_f32_e32 v155, v83, v149
	v_mul_f32_e32 v149, v91, v149
	v_fmac_f32_e32 v149, v90, v148
	v_fmac_f32_e32 v155, v82, v148
	v_fmac_f32_e32 v149, v118, v150
	v_fmac_f32_e32 v155, v106, v150
	v_fmac_f32_e32 v149, v119, v151
	v_fmac_f32_e32 v155, v107, v151
	v_add_f32_e32 v154, v154, v149
	ds_read2st64_b32 v[148:149], v138 offset0:184 offset1:185
	ds_read2st64_b32 v[150:151], v138 offset0:186 offset1:187
	v_add_f32_e32 v153, v153, v155
	s_waitcnt lgkmcnt(0)
	v_mul_f32_e32 v155, v69, v149
	v_fmac_f32_e32 v155, v68, v148
	s_waitcnt lgkmcnt(0)
	v_fmac_f32_e32 v155, v96, v150
	v_fmac_f32_e32 v155, v97, v151
	v_add_f32_e32 v146, v146, v155
	v_mul_f32_e32 v155, v73, v149
	v_fmac_f32_e32 v155, v72, v148
	v_fmac_f32_e32 v155, v92, v150
	v_fmac_f32_e32 v155, v93, v151
	v_add_f32_e32 v152, v152, v155
	v_mul_f32_e32 v155, v81, v149
	v_mul_f32_e32 v149, v89, v149
	v_fmac_f32_e32 v149, v88, v148
	v_fmac_f32_e32 v155, v80, v148
	v_fmac_f32_e32 v149, v108, v150
	v_fmac_f32_e32 v155, v100, v150
	v_fmac_f32_e32 v149, v109, v151
	v_fmac_f32_e32 v155, v101, v151
	v_add_f32_e32 v154, v154, v149
	ds_read2st64_b32 v[148:149], v138 offset0:188 offset1:189
	ds_read2st64_b32 v[150:151], v138 offset0:190 offset1:191
	v_add_f32_e32 v153, v153, v155
	s_waitcnt lgkmcnt(0)
	v_mul_f32_e32 v155, v85, v149
	v_fmac_f32_e32 v155, v84, v148
	s_waitcnt lgkmcnt(0)
	v_fmac_f32_e32 v155, v126, v150
	v_fmac_f32_e32 v155, v127, v151
	v_add_f32_e32 v171, v146, v155
	v_mul_f32_e32 v146, v95, v149
	v_fmac_f32_e32 v146, v94, v148
	v_fmac_f32_e32 v146, v124, v150
	v_fmac_f32_e32 v146, v125, v151
	v_add_f32_e32 v170, v152, v146
	v_mul_f32_e32 v146, v115, v149
	v_fmac_f32_e32 v146, v114, v148
	v_fmac_f32_e32 v146, v128, v150
	v_fmac_f32_e32 v146, v129, v151
	v_add_f32_e32 v169, v153, v146
	v_mul_f32_e32 v146, v123, v149
	v_fmac_f32_e32 v146, v122, v148
	v_fmac_f32_e32 v146, v130, v150
	v_fmac_f32_e32 v146, v131, v151
	ds_read2st64_b32 v[148:149], v138 offset0:192 offset1:193
	ds_read2st64_b32 v[150:151], v138 offset0:194 offset1:195
	v_add_f32_e32 v168, v154, v146
	s_waitcnt lgkmcnt(0)
	v_mul_f32_e32 v146, v79, v149
	v_mul_f32_e32 v152, v77, v149
	v_mul_f32_e32 v153, v87, v149
	v_mul_f32_e32 v149, v99, v149
	v_fmac_f32_e32 v149, v98, v148
	v_fmac_f32_e32 v146, v78, v148
	v_fmac_f32_e32 v152, v76, v148
	v_fmac_f32_e32 v153, v86, v148
	s_waitcnt lgkmcnt(0)
	v_fmac_f32_e32 v149, v120, v150
	v_fmac_f32_e32 v146, v112, v150
	v_fmac_f32_e32 v152, v110, v150
	v_fmac_f32_e32 v153, v116, v150
	v_fmac_f32_e32 v149, v121, v151
	v_fmac_f32_e32 v146, v113, v151
	v_fmac_f32_e32 v152, v111, v151
	v_fmac_f32_e32 v153, v117, v151
	v_add_f32_e32 v154, 0, v149
	ds_read2st64_b32 v[148:149], v138 offset0:196 offset1:197
	ds_read2st64_b32 v[150:151], v138 offset0:198 offset1:199
	v_add_f32_e32 v146, 0, v146
	v_add_f32_e32 v152, 0, v152
	v_add_f32_e32 v153, 0, v153
	s_waitcnt lgkmcnt(0)
; #define LAS __attribute__((address_space(3)))
; __device__ __forceinline__ void phase_ma(const Params& p, Frame& F, int l, const bool fd, const float* xin32) {
;     ...
;             for (int ei = 0; ei < 8; ++ei) { const int e = 8 * hh + ei; float a0 = 0.f, a1 = 0.f, a2 = 0.f, a3 = 0.f;
; #pragma unroll
;                 for (int j = 0; j < 4; ++j) { const LAS float* w = wrp + (((e * 4 + j) * 4) << 6) + F.lane; const float w0 = w[0], w1 = w[64], w2 = w[128], w3 = w[192];
;                     a0 += h[0][j].x * w0 + h[0][j].y * w1 + h[0][j].z * w2 + h[0][j].w * w3; a1 += h[1][j].x * w0 + h[1][j].y * w1 + h[1][j].z * w2 + h[1][j].w * w3;
;                     a2 += h[2][j].x * w0 + h[2][j].y * w1 + h[2][j].z * w2 + h[2][j].w * w3; a3 += h[3][j].x * w0 + h[3][j].y * w1 + h[3][j].z * w2 + h[3][j].w * w3; }
;                 v[0][ei] = a0; v[1][ei] = a1; v[2][ei] = a2; v[3][ei] = a3; }
	v_mul_f32_e32 v155, v71, v149
	v_fmac_f32_e32 v155, v70, v148
	s_waitcnt lgkmcnt(0)
	v_fmac_f32_e32 v155, v104, v150
	v_fmac_f32_e32 v155, v105, v151
	v_add_f32_e32 v146, v146, v155
	v_mul_f32_e32 v155, v75, v149
	v_fmac_f32_e32 v155, v74, v148
	v_fmac_f32_e32 v155, v102, v150
	v_fmac_f32_e32 v155, v103, v151
	v_add_f32_e32 v152, v152, v155
	v_mul_f32_e32 v155, v83, v149
	v_mul_f32_e32 v149, v91, v149
	v_fmac_f32_e32 v149, v90, v148
	v_fmac_f32_e32 v155, v82, v148
	v_fmac_f32_e32 v149, v118, v150
	v_fmac_f32_e32 v155, v106, v150
	v_fmac_f32_e32 v149, v119, v151
	v_fmac_f32_e32 v155, v107, v151
	v_add_f32_e32 v154, v154, v149
	ds_read2st64_b32 v[148:149], v138 offset0:200 offset1:201
	ds_read2st64_b32 v[150:151], v138 offset0:202 offset1:203
	v_add_f32_e32 v153, v153, v155
	s_waitcnt lgkmcnt(0)
	v_mul_f32_e32 v155, v69, v149
	v_fmac_f32_e32 v155, v68, v148
	s_waitcnt lgkmcnt(0)
	v_fmac_f32_e32 v155, v96, v150
	v_fmac_f32_e32 v155, v97, v151
	v_add_f32_e32 v146, v146, v155
	v_mul_f32_e32 v155, v73, v149
	v_fmac_f32_e32 v155, v72, v148
	v_fmac_f32_e32 v155, v92, v150
	v_fmac_f32_e32 v155, v93, v151
	v_add_f32_e32 v152, v152, v155
	v_mul_f32_e32 v155, v81, v149
	v_mul_f32_e32 v149, v89, v149
	v_fmac_f32_e32 v149, v88, v148
	v_fmac_f32_e32 v155, v80, v148
	v_fmac_f32_e32 v149, v108, v150
	v_fmac_f32_e32 v155, v100, v150
	v_fmac_f32_e32 v149, v109, v151
	v_fmac_f32_e32 v155, v101, v151
	v_add_f32_e32 v154, v154, v149
	ds_read2st64_b32 v[148:149], v138 offset0:204 offset1:205
	ds_read2st64_b32 v[150:151], v138 offset0:206 offset1:207
	v_add_f32_e32 v153, v153, v155
	s_waitcnt lgkmcnt(0)
	v_mul_f32_e32 v155, v85, v149
	v_fmac_f32_e32 v155, v84, v148
	s_waitcnt lgkmcnt(0)
	v_fmac_f32_e32 v155, v126, v150
	v_fmac_f32_e32 v155, v127, v151
	v_add_f32_e32 v175, v146, v155
	v_mul_f32_e32 v146, v95, v149
	v_fmac_f32_e32 v146, v94, v148
	v_fmac_f32_e32 v146, v124, v150
	v_fmac_f32_e32 v146, v125, v151
	v_add_f32_e32 v174, v152, v146
	v_mul_f32_e32 v146, v115, v149
	v_fmac_f32_e32 v146, v114, v148
	v_fmac_f32_e32 v146, v128, v150
	v_fmac_f32_e32 v146, v129, v151
	v_add_f32_e32 v173, v153, v146
	v_mul_f32_e32 v146, v123, v149
	v_fmac_f32_e32 v146, v122, v148
	v_fmac_f32_e32 v146, v130, v150
	v_fmac_f32_e32 v146, v131, v151
	ds_read2st64_b32 v[148:149], v138 offset0:208 offset1:209
	ds_read2st64_b32 v[150:151], v138 offset0:210 offset1:211
	v_add_f32_e32 v172, v154, v146
	s_waitcnt lgkmcnt(0)
	v_mul_f32_e32 v146, v79, v149
	v_mul_f32_e32 v152, v77, v149
	v_mul_f32_e32 v153, v87, v149
	v_mul_f32_e32 v149, v99, v149
	v_fmac_f32_e32 v149, v98, v148
	v_fmac_f32_e32 v146, v78, v148
	v_fmac_f32_e32 v152, v76, v148
	v_fmac_f32_e32 v153, v86, v148
	s_waitcnt lgkmcnt(0)
	v_fmac_f32_e32 v149, v120, v150
	v_fmac_f32_e32 v146, v112, v150
	v_fmac_f32_e32 v152, v110, v150
	v_fmac_f32_e32 v153, v116, v150
	v_fmac_f32_e32 v149, v121, v151
	v_fmac_f32_e32 v146, v113, v151
	v_fmac_f32_e32 v152, v111, v151
	v_fmac_f32_e32 v153, v117, v151
	v_add_f32_e32 v154, 0, v149
	ds_read2st64_b32 v[148:149], v138 offset0:212 offset1:213
	ds_read2st64_b32 v[150:151], v138 offset0:214 offset1:215
	v_add_f32_e32 v146, 0, v146
	v_add_f32_e32 v152, 0, v152
	v_add_f32_e32 v153, 0, v153
	s_waitcnt lgkmcnt(0)
	v_mul_f32_e32 v155, v71, v149
	v_fmac_f32_e32 v155, v70, v148
	s_waitcnt lgkmcnt(0)
	v_fmac_f32_e32 v155, v104, v150
	v_fmac_f32_e32 v155, v105, v151
	v_add_f32_e32 v146, v146, v155
	v_mul_f32_e32 v155, v75, v149
	v_fmac_f32_e32 v155, v74, v148
	v_fmac_f32_e32 v155, v102, v150
	v_fmac_f32_e32 v155, v103, v151
	v_add_f32_e32 v152, v152, v155
	v_mul_f32_e32 v155, v83, v149
	v_mul_f32_e32 v149, v91, v149
	v_fmac_f32_e32 v149, v90, v148
	v_fmac_f32_e32 v155, v82, v148
	v_fmac_f32_e32 v149, v118, v150
	v_fmac_f32_e32 v155, v106, v150
	v_fmac_f32_e32 v149, v119, v151
	v_fmac_f32_e32 v155, v107, v151
	v_add_f32_e32 v154, v154, v149
	ds_read2st64_b32 v[148:149], v138 offset0:216 offset1:217
	ds_read2st64_b32 v[150:151], v138 offset0:218 offset1:219
	v_add_f32_e32 v153, v153, v155
	s_waitcnt lgkmcnt(0)
	v_mul_f32_e32 v155, v69, v149
	v_fmac_f32_e32 v155, v68, v148
	s_waitcnt lgkmcnt(0)
	v_fmac_f32_e32 v155, v96, v150
	v_fmac_f32_e32 v155, v97, v151
	v_add_f32_e32 v146, v146, v155
	v_mul_f32_e32 v155, v73, v149
	v_fmac_f32_e32 v155, v72, v148
	v_fmac_f32_e32 v155, v92, v150
	v_fmac_f32_e32 v155, v93, v151
	v_add_f32_e32 v152, v152, v155
	v_mul_f32_e32 v155, v81, v149
	v_mul_f32_e32 v149, v89, v149
	v_fmac_f32_e32 v149, v88, v148
	v_fmac_f32_e32 v155, v80, v148
	v_fmac_f32_e32 v149, v108, v150
	v_fmac_f32_e32 v155, v100, v150
	v_fmac_f32_e32 v149, v109, v151
	v_fmac_f32_e32 v155, v101, v151
	v_add_f32_e32 v154, v154, v149
	ds_read2st64_b32 v[148:149], v138 offset0:220 offset1:221
	ds_read2st64_b32 v[150:151], v138 offset0:222 offset1:223
	v_add_f32_e32 v153, v153, v155
	s_waitcnt lgkmcnt(0)
	v_mul_f32_e32 v155, v85, v149
	v_fmac_f32_e32 v155, v84, v148
	s_waitcnt lgkmcnt(0)
	v_fmac_f32_e32 v155, v126, v150
	v_fmac_f32_e32 v155, v127, v151
	v_add_f32_e32 v180, v146, v155
	v_mul_f32_e32 v146, v95, v149
	v_fmac_f32_e32 v146, v94, v148
	v_fmac_f32_e32 v146, v124, v150
	v_fmac_f32_e32 v146, v125, v151
	v_add_f32_e32 v178, v152, v146
	v_mul_f32_e32 v146, v115, v149
	v_fmac_f32_e32 v146, v114, v148
	v_fmac_f32_e32 v146, v128, v150
	v_fmac_f32_e32 v146, v129, v151
	v_add_f32_e32 v177, v153, v146
	v_mul_f32_e32 v146, v123, v149
	v_fmac_f32_e32 v146, v122, v148
	v_fmac_f32_e32 v146, v130, v150
	v_fmac_f32_e32 v146, v131, v151
	ds_read2st64_b32 v[148:149], v138 offset0:224 offset1:225
	ds_read2st64_b32 v[150:151], v138 offset0:226 offset1:227
	v_add_f32_e32 v176, v154, v146
	s_waitcnt lgkmcnt(0)
; #define LAS __attribute__((address_space(3)))
; __device__ __forceinline__ void phase_ma(const Params& p, Frame& F, int l, const bool fd, const float* xin32) {
;     ...
;             for (int ei = 0; ei < 8; ++ei) { const int e = 8 * hh + ei; float a0 = 0.f, a1 = 0.f, a2 = 0.f, a3 = 0.f;
; #pragma unroll
;                 for (int j = 0; j < 4; ++j) { const LAS float* w = wrp + (((e * 4 + j) * 4) << 6) + F.lane; const float w0 = w[0], w1 = w[64], w2 = w[128], w3 = w[192];
;                     a0 += h[0][j].x * w0 + h[0][j].y * w1 + h[0][j].z * w2 + h[0][j].w * w3; a1 += h[1][j].x * w0 + h[1][j].y * w1 + h[1][j].z * w2 + h[1][j].w * w3;
;                     a2 += h[2][j].x * w0 + h[2][j].y * w1 + h[2][j].z * w2 + h[2][j].w * w3; a3 += h[3][j].x * w0 + h[3][j].y * w1 + h[3][j].z * w2 + h[3][j].w * w3; }
;                 v[0][ei] = a0; v[1][ei] = a1; v[2][ei] = a2; v[3][ei] = a3; }
	v_mul_f32_e32 v146, v79, v149
	v_mul_f32_e32 v152, v77, v149
	v_mul_f32_e32 v153, v87, v149
	v_mul_f32_e32 v149, v99, v149
	v_fmac_f32_e32 v149, v98, v148
	v_fmac_f32_e32 v146, v78, v148
	v_fmac_f32_e32 v152, v76, v148
	v_fmac_f32_e32 v153, v86, v148
	s_waitcnt lgkmcnt(0)
	v_fmac_f32_e32 v149, v120, v150
	v_fmac_f32_e32 v146, v112, v150
	v_fmac_f32_e32 v152, v110, v150
	v_fmac_f32_e32 v153, v116, v150
	v_fmac_f32_e32 v149, v121, v151
	v_fmac_f32_e32 v146, v113, v151
	v_fmac_f32_e32 v152, v111, v151
	v_fmac_f32_e32 v153, v117, v151
	v_add_f32_e32 v154, 0, v149
	ds_read2st64_b32 v[148:149], v138 offset0:228 offset1:229
	ds_read2st64_b32 v[150:151], v138 offset0:230 offset1:231
	v_add_f32_e32 v146, 0, v146
	v_add_f32_e32 v152, 0, v152
	v_add_f32_e32 v153, 0, v153
	s_waitcnt lgkmcnt(0)
	v_mul_f32_e32 v155, v71, v149
	v_fmac_f32_e32 v155, v70, v148
	s_waitcnt lgkmcnt(0)
	v_fmac_f32_e32 v155, v104, v150
	v_fmac_f32_e32 v155, v105, v151
	v_add_f32_e32 v146, v146, v155
	v_mul_f32_e32 v155, v75, v149
	v_fmac_f32_e32 v155, v74, v148
	v_fmac_f32_e32 v155, v102, v150
	v_fmac_f32_e32 v155, v103, v151
	v_add_f32_e32 v152, v152, v155
	v_mul_f32_e32 v155, v83, v149
	v_mul_f32_e32 v149, v91, v149
	v_fmac_f32_e32 v149, v90, v148
	v_fmac_f32_e32 v155, v82, v148
	v_fmac_f32_e32 v149, v118, v150
	v_fmac_f32_e32 v155, v106, v150
	v_fmac_f32_e32 v149, v119, v151
	v_fmac_f32_e32 v155, v107, v151
	v_add_f32_e32 v154, v154, v149
	ds_read2st64_b32 v[148:149], v138 offset0:232 offset1:233
	ds_read2st64_b32 v[150:151], v138 offset0:234 offset1:235
	v_add_f32_e32 v153, v153, v155
	s_waitcnt lgkmcnt(0)
	v_mul_f32_e32 v155, v69, v149
	v_fmac_f32_e32 v155, v68, v148
	s_waitcnt lgkmcnt(0)
	v_fmac_f32_e32 v155, v96, v150
	v_fmac_f32_e32 v155, v97, v151
	v_add_f32_e32 v146, v146, v155
	v_mul_f32_e32 v155, v73, v149
	v_fmac_f32_e32 v155, v72, v148
	v_fmac_f32_e32 v155, v92, v150
	v_fmac_f32_e32 v155, v93, v151
	v_add_f32_e32 v152, v152, v155
	v_mul_f32_e32 v155, v81, v149
	v_mul_f32_e32 v149, v89, v149
	v_fmac_f32_e32 v149, v88, v148
	v_fmac_f32_e32 v155, v80, v148
	v_fmac_f32_e32 v149, v108, v150
	v_fmac_f32_e32 v155, v100, v150
	v_fmac_f32_e32 v149, v109, v151
	v_fmac_f32_e32 v155, v101, v151
	v_add_f32_e32 v154, v154, v149
	ds_read2st64_b32 v[148:149], v138 offset0:236 offset1:237
	ds_read2st64_b32 v[150:151], v138 offset0:238 offset1:239
	v_add_f32_e32 v153, v153, v155
	s_waitcnt lgkmcnt(0)
	v_mul_f32_e32 v155, v85, v149
	v_fmac_f32_e32 v155, v84, v148
	s_waitcnt lgkmcnt(0)
	v_fmac_f32_e32 v155, v126, v150
	v_fmac_f32_e32 v155, v127, v151
	v_add_f32_e32 v146, v146, v155
	v_mul_f32_e32 v155, v95, v149
	v_fmac_f32_e32 v155, v94, v148
	v_fmac_f32_e32 v155, v124, v150
	v_fmac_f32_e32 v155, v125, v151
	v_add_f32_e32 v186, v152, v155
	v_mul_f32_e32 v152, v115, v149
	v_mul_f32_e32 v149, v123, v149
	v_fmac_f32_e32 v149, v122, v148
	v_fmac_f32_e32 v152, v114, v148
	v_fmac_f32_e32 v149, v130, v150
	v_fmac_f32_e32 v152, v128, v150
	v_fmac_f32_e32 v149, v131, v151
	v_fmac_f32_e32 v152, v129, v151
	v_add_f32_e32 v182, v154, v149
	ds_read2st64_b32 v[148:149], v138 offset0:240 offset1:241
	ds_read2st64_b32 v[150:151], v138 offset0:242 offset1:243
	v_add_f32_e32 v184, v153, v152
	s_waitcnt lgkmcnt(0)
	v_mul_f32_e32 v152, v79, v149
	v_mul_f32_e32 v153, v77, v149
	v_mul_f32_e32 v154, v87, v149
	v_mul_f32_e32 v149, v99, v149
	v_fmac_f32_e32 v149, v98, v148
	v_fmac_f32_e32 v152, v78, v148
	v_fmac_f32_e32 v153, v76, v148
	v_fmac_f32_e32 v154, v86, v148
	s_waitcnt lgkmcnt(0)
	v_fmac_f32_e32 v149, v120, v150
	v_fmac_f32_e32 v152, v112, v150
	v_fmac_f32_e32 v153, v110, v150
	v_fmac_f32_e32 v154, v116, v150
	v_fmac_f32_e32 v149, v121, v151
	v_fmac_f32_e32 v152, v113, v151
	v_fmac_f32_e32 v153, v111, v151
	v_fmac_f32_e32 v154, v117, v151
	v_add_f32_e32 v155, 0, v149
	ds_read2st64_b32 v[148:149], v138 offset0:244 offset1:245
	ds_read2st64_b32 v[150:151], v138 offset0:246 offset1:247
	v_add_f32_e32 v152, 0, v152
	v_add_f32_e32 v153, 0, v153
	v_add_f32_e32 v154, 0, v154
	s_waitcnt lgkmcnt(0)
	v_mul_f32_e32 v158, v71, v149
	v_fmac_f32_e32 v158, v70, v148
	s_waitcnt lgkmcnt(0)
	v_fmac_f32_e32 v158, v104, v150
	v_fmac_f32_e32 v158, v105, v151
	v_add_f32_e32 v152, v152, v158
	v_mul_f32_e32 v158, v75, v149
	v_fmac_f32_e32 v158, v74, v148
	v_fmac_f32_e32 v158, v102, v150
	v_fmac_f32_e32 v158, v103, v151
	v_add_f32_e32 v153, v153, v158
	v_mul_f32_e32 v158, v83, v149
	v_mul_f32_e32 v149, v91, v149
	v_fmac_f32_e32 v149, v90, v148
	v_fmac_f32_e32 v158, v82, v148
	v_fmac_f32_e32 v149, v118, v150
	v_fmac_f32_e32 v158, v106, v150
	v_fmac_f32_e32 v149, v119, v151
	v_fmac_f32_e32 v158, v107, v151
	v_add_f32_e32 v155, v155, v149
	ds_read2st64_b32 v[148:149], v138 offset0:248 offset1:249
	ds_read2st64_b32 v[150:151], v138 offset0:250 offset1:251
	v_add_f32_e32 v154, v154, v158
	s_waitcnt lgkmcnt(0)
	v_mul_f32_e32 v158, v69, v149
	v_fmac_f32_e32 v158, v68, v148
	s_waitcnt lgkmcnt(0)
	v_fmac_f32_e32 v158, v96, v150
	v_fmac_f32_e32 v158, v97, v151
	v_add_f32_e32 v152, v152, v158
	v_mul_f32_e32 v158, v73, v149
	v_fmac_f32_e32 v158, v72, v148
	v_fmac_f32_e32 v158, v92, v150
	v_fmac_f32_e32 v158, v93, v151
	v_add_f32_e32 v153, v153, v158
	v_mul_f32_e32 v158, v81, v149
	v_mul_f32_e32 v149, v89, v149
	v_fmac_f32_e32 v149, v88, v148
	v_fmac_f32_e32 v158, v80, v148
	v_fmac_f32_e32 v149, v108, v150
	v_fmac_f32_e32 v158, v100, v150
	v_fmac_f32_e32 v149, v109, v151
	v_fmac_f32_e32 v158, v101, v151
	v_add_f32_e32 v155, v155, v149
	ds_read2st64_b32 v[148:149], v138 offset0:252 offset1:253
	ds_read2st64_b32 v[150:151], v138 offset0:254 offset1:255
	v_add_f32_e32 v154, v154, v158
	s_waitcnt lgkmcnt(0)
; __device__ __forceinline__ float shx(float v, int o, int lane) { return __builtin_bit_cast(float, __builtin_amdgcn_ds_bpermute((lane ^ o) << 2, __builtin_bit_cast(int, v))); }
; __device__ __forceinline__ void phase_ma(const Params& p, Frame& F, int l, const bool fd, const float* xin32) {
;     ...
;             for (int r = 0; r < 4; ++r) { float t4[4], t2[2];
;                 { const bool hi = (F.lane & 32) != 0;
; #pragma unroll
;                   for (int i = 0; i < 4; ++i) { const float send = hi ? v[r][i] : v[r][i + 4], keep = hi ? v[r][i + 4] : v[r][i]; t4[i] = keep + shx(send, 32, F.lane); } }
;                 { const bool hi = (F.lane & 16) != 0;
; #pragma unroll
;                   for (int i = 0; i < 2; ++i) { const float send = hi ? t4[i] : t4[i + 2], keep = hi ? t4[i + 2] : t4[i]; t2[i] = keep + shx(send, 16, F.lane); } }
;                 { const bool hi = (F.lane & 8) != 0; const float send = hi ? t2[0] : t2[1], keep = hi ? t2[1] : t2[0]; th2[r][hh] = keep + shx(send, 8, F.lane); } }
;         }
; #pragma unroll
;         for (int r = 0; r < 4; ++r) { float t1;
;             { const bool hi = (F.lane & 4) != 0; const float send = hi ? th2[r][0] : th2[r][1], keep = hi ? th2[r][1] : th2[r][0]; t1 = keep + shx(send, 4, F.lane); }
;             t1 += shx(t1, 1, F.lane); t1 += shx(t1, 2, F.lane);
;             float mx = t1;
; #pragma unroll
;             for (int o = 4; o < 64; o <<= 1) mx = fmaxf(mx, shx(mx, o, F.lane));
;             const float pe = expf(t1 - mx); float sum = pe;
; #pragma unroll
;             for (int o = 4; o < 64; o <<= 1) sum += shx(sum, o, F.lane);
;             const int e = ((F.lane >> 2) & 1) * 8 + ((F.lane >> 5) & 1) * 4 + ((F.lane >> 4) & 1) * 2 + ((F.lane >> 3) & 1);
;             if ((F.lane & 3) == 0) aff[((size_t)b * NE + e) * S + s0 + r * rstep] = pe / sum; }
	v_mul_f32_e32 v158, v85, v149
	v_fmac_f32_e32 v158, v84, v148
	s_waitcnt lgkmcnt(0)
	v_fmac_f32_e32 v158, v126, v150
	v_fmac_f32_e32 v158, v127, v151
	v_add_f32_e32 v152, v152, v158
	v_mul_f32_e32 v158, v95, v149
	v_fmac_f32_e32 v158, v94, v148
	v_fmac_f32_e32 v158, v124, v150
	v_fmac_f32_e32 v158, v125, v151
	v_add_f32_e32 v153, v153, v158
	v_mul_f32_e32 v158, v115, v149
	v_mul_f32_e32 v149, v123, v149
	v_fmac_f32_e32 v149, v122, v148
	v_fmac_f32_e32 v149, v130, v150
	v_fmac_f32_e32 v149, v131, v151
	v_fmac_f32_e32 v158, v114, v148
	v_add_f32_e32 v148, v155, v149
	v_permlane32_swap_b32 v144, v175
	v_add_f32_e32 v144, v144, v175
	v_fmac_f32_e32 v158, v128, v150
	v_fmac_f32_e32 v158, v129, v151
	s_waitcnt lgkmcnt(0)
	v_permlane32_swap_b32 v163, v180
	v_add_f32_e32 v149, v163, v180
	v_add_f32_e32 v154, v154, v158
	s_waitcnt lgkmcnt(0)
	v_permlane32_swap_b32 v167, v146
	v_add_f32_e32 v146, v167, v146
	s_waitcnt lgkmcnt(0)
	v_permlane32_swap_b32 v171, v152
	v_add_f32_e32 v150, v171, v152
	s_waitcnt lgkmcnt(0)
	v_permlane16_swap_b32 v144, v146
	v_add_f32_e32 v144, v144, v146
	s_waitcnt lgkmcnt(0)
	v_permlane16_swap_b32 v149, v150
	v_add_f32_e32 v146, v149, v150
	s_waitcnt lgkmcnt(0)
	v_cndmask_b32_e64 v149, v144, v146, s[42:43]
	v_cndmask_b32_e64 v144, v146, v144, s[42:43]
	s_nop 0
	v_mov_b32_dpp v146, v149 row_ror:8 row_mask:0xf bank_mask:0xf
	s_waitcnt lgkmcnt(0)
	v_add_f32_e32 v146, v144, v146
	s_nop 2
	v_permlane32_swap_b32 v143, v174
	v_add_f32_e32 v143, v143, v174
	s_waitcnt lgkmcnt(0)
	v_permlane32_swap_b32 v162, v178
	v_add_f32_e32 v144, v162, v178
	s_waitcnt lgkmcnt(0)
	v_permlane32_swap_b32 v166, v186
	v_add_f32_e32 v149, v166, v186
	s_waitcnt lgkmcnt(0)
	v_permlane32_swap_b32 v170, v153
	v_add_f32_e32 v150, v170, v153
	s_waitcnt lgkmcnt(0)
	v_permlane16_swap_b32 v143, v149
	v_add_f32_e32 v162, v143, v149
	s_waitcnt lgkmcnt(0)
	v_permlane16_swap_b32 v144, v150
	v_add_f32_e32 v166, v144, v150
	s_waitcnt lgkmcnt(0)
	v_cndmask_b32_e64 v143, v162, v166, s[42:43]
	s_nop 1
	v_mov_b32_dpp v167, v143 row_ror:8 row_mask:0xf bank_mask:0xf
	s_nop 3
	v_permlane32_swap_b32 v142, v173
	v_add_f32_e32 v142, v142, v173
	s_waitcnt lgkmcnt(0)
	v_permlane32_swap_b32 v156, v177
	v_add_f32_e32 v143, v156, v177
	s_waitcnt lgkmcnt(0)
	v_permlane32_swap_b32 v165, v184
	v_add_f32_e32 v144, v165, v184
	s_waitcnt lgkmcnt(0)
	v_permlane32_swap_b32 v169, v154
	v_add_f32_e32 v149, v169, v154
	s_waitcnt lgkmcnt(0)
	v_permlane16_swap_b32 v142, v144
	v_add_f32_e32 v144, v142, v144
	s_waitcnt lgkmcnt(0)
	v_permlane16_swap_b32 v143, v149
	v_add_f32_e32 v156, v143, v149
	s_waitcnt lgkmcnt(0)
	v_cndmask_b32_e64 v142, v144, v156, s[42:43]
	s_nop 1
	v_mov_b32_dpp v163, v142 row_ror:8 row_mask:0xf bank_mask:0xf
	s_nop 3
	v_permlane32_swap_b32 v141, v172
	v_add_f32_e32 v141, v141, v172
	s_waitcnt lgkmcnt(0)
	v_permlane32_swap_b32 v147, v176
	v_add_f32_e32 v142, v147, v176
	s_waitcnt lgkmcnt(0)
	v_permlane32_swap_b32 v164, v182
	v_add_f32_e32 v143, v164, v182
	s_waitcnt lgkmcnt(0)
	v_permlane32_swap_b32 v168, v148
	v_add_f32_e32 v147, v168, v148
	s_waitcnt lgkmcnt(0)
	v_permlane16_swap_b32 v141, v143
	v_add_f32_e32 v141, v141, v143
	s_waitcnt lgkmcnt(0)
	v_cndmask_b32_e64 v143, v142, v147, s[40:41]
	v_cndmask_b32_e64 v142, v147, v142, s[40:41]
	v_cndmask_b32_e64 v147, v140, v146, s[44:45]
	v_cndmask_b32_e64 v140, v146, v140, s[44:45]
	s_nop 0
	v_mov_b32_dpp v146, v147 quad_perm:[3,2,1,0] row_mask:0xf bank_mask:0xf
	s_nop 1
	v_mov_b32_dpp v146, v146 row_half_mirror row_mask:0xf bank_mask:0xf
	v_mov_b32_e32 v143, v143
	v_mov_b32_e32 v191, v143
	s_nop 1
	v_permlane16_swap_b32 v143, v191
	v_cndmask_b32_e64 v143, v143, v191, s[40:41]
	s_waitcnt lgkmcnt(0)
	v_add_f32_e32 v140, v140, v146
	s_nop 1
	v_mov_b32_dpp v146, v140 quad_perm:[1,0,3,2] row_mask:0xf bank_mask:0xf
	s_waitcnt lgkmcnt(0)
	v_add_f32_e32 v142, v142, v143
	v_cndmask_b32_e64 v143, v141, v142, s[42:43]
	s_nop 1
	v_mov_b32_dpp v143, v143 row_ror:8 row_mask:0xf bank_mask:0xf
	s_waitcnt lgkmcnt(0)
	v_add_f32_e32 v140, v140, v146
	s_nop 1
	v_mov_b32_dpp v146, v140 quad_perm:[2,3,0,1] row_mask:0xf bank_mask:0xf
	s_waitcnt lgkmcnt(0)
	v_add_f32_e32 v140, v140, v146
	s_nop 1
	v_mov_b32_dpp v146, v140 quad_perm:[3,2,1,0] row_mask:0xf bank_mask:0xf
	s_nop 1
	v_mov_b32_dpp v146, v146 row_half_mirror row_mask:0xf bank_mask:0xf
	s_waitcnt lgkmcnt(0)
	v_max_f32_e32 v146, v146, v146
	v_max_f32_e32 v146, v140, v146
	s_nop 1
	v_mov_b32_dpp v147, v146 row_ror:8 row_mask:0xf bank_mask:0xf
	s_waitcnt lgkmcnt(0)
	v_max_f32_e32 v147, v147, v147
	v_max_f32_e32 v146, v146, v147
	v_mov_b32_e32 v147, v146
	s_nop 1
	v_permlane16_swap_b32 v147, v146
	s_waitcnt lgkmcnt(0)
	v_max_f32_e32 v147, v147, v147
	v_max_f32_e32 v146, v146, v147
	v_mov_b32_e32 v147, v146
	s_nop 1
	v_permlane32_swap_b32 v147, v146
	s_waitcnt lgkmcnt(0)
	v_max_f32_e32 v147, v147, v147
	v_max_f32_e32 v146, v146, v147
	v_sub_f32_e32 v140, v140, v146
	v_mul_f32_e32 v146, 0x3fb8aa3b, v140
	v_fma_f32 v147, v140, s2, -v146
	v_rndne_f32_e32 v148, v146
	v_fmac_f32_e32 v147, 0x32a5705f, v140
	v_sub_f32_e32 v146, v146, v148
	v_add_f32_e32 v146, v146, v147
	v_exp_f32_e32 v146, v146
	v_cvt_i32_f32_e32 v147, v148
	s_mov_b32 s2, 0xc2ce8ed0
	v_cmp_ngt_f32_e32 vcc, s2, v140
	s_mov_b32 s2, 0x42b17218
	v_ldexp_f32 v146, v146, v147
	v_cndmask_b32_e32 v146, 0, v146, vcc
	v_cmp_nlt_f32_e32 vcc, s2, v140
	s_nop 1
	v_cndmask_b32_e32 v140, v250, v146, vcc
	s_nop 1
	v_mov_b32_dpp v146, v140 quad_perm:[3,2,1,0] row_mask:0xf bank_mask:0xf
	s_nop 1
	v_mov_b32_dpp v146, v146 row_half_mirror row_mask:0xf bank_mask:0xf
	s_waitcnt lgkmcnt(0)
	v_add_f32_e32 v146, v140, v146
	s_nop 1
	v_mov_b32_dpp v147, v146 row_ror:8 row_mask:0xf bank_mask:0xf
	s_waitcnt lgkmcnt(0)
	v_add_f32_e32 v146, v146, v147
	v_mov_b32_e32 v147, v146
	s_nop 1
	v_permlane16_swap_b32 v147, v146
	s_waitcnt lgkmcnt(0)
	v_add_f32_e32 v147, v146, v147
	v_mov_b32_e32 v164, v147
	v_mov_b32_e32 v192, v147
	s_nop 1
	v_permlane32_swap_b32 v164, v192
	v_cndmask_b32_e64 v164, v164, v192, s[38:39]
	s_and_saveexec_b64 s[2:3], s[0:1]
	s_cbranch_execz .LBB0_842
	s_waitcnt lgkmcnt(0)
	v_add_f32_e32 v146, v147, v164
	v_div_scale_f32 v147, s[8:9], v146, v146, v140
	v_rcp_f32_e32 v148, v147
	v_div_scale_f32 v149, vcc, v140, v146, v140
	v_fma_f32 v150, -v147, v148, 1.0
	v_fmac_f32_e32 v148, v150, v148
	v_mul_f32_e32 v150, v149, v148
	v_fma_f32 v151, -v147, v150, v149
	v_fmac_f32_e32 v150, v151, v148
	v_fma_f32 v147, -v147, v150, v149
	v_div_fmas_f32 v147, v147, v148, v150
	v_div_fixup_f32 v140, v147, v146, v140
	flat_store_dword v[62:63], v140
; __device__ __forceinline__ float shx(float v, int o, int lane) { return __builtin_bit_cast(float, __builtin_amdgcn_ds_bpermute((lane ^ o) << 2, __builtin_bit_cast(int, v))); }
; __device__ __forceinline__ void phase_ma(const Params& p, Frame& F, int l, const bool fd, const float* xin32) {
;     ...
;         for (int r = 0; r < 4; ++r) { float t1;
;             { const bool hi = (F.lane & 4) != 0; const float send = hi ? th2[r][0] : th2[r][1], keep = hi ? th2[r][1] : th2[r][0]; t1 = keep + shx(send, 4, F.lane); }
;             t1 += shx(t1, 1, F.lane); t1 += shx(t1, 2, F.lane);
;             float mx = t1;
; #pragma unroll
;             for (int o = 4; o < 64; o <<= 1) mx = fmaxf(mx, shx(mx, o, F.lane));
;             const float pe = expf(t1 - mx); float sum = pe;
; #pragma unroll
;             for (int o = 4; o < 64; o <<= 1) sum += shx(sum, o, F.lane);
;             const int e = ((F.lane >> 2) & 1) * 8 + ((F.lane >> 5) & 1) * 4 + ((F.lane >> 4) & 1) * 2 + ((F.lane >> 3) & 1);
;             if ((F.lane & 3) == 0) aff[((size_t)b * NE + e) * S + s0 + r * rstep] = pe / sum; }
.LBB0_842:
	s_or_b64 exec, exec, s[2:3]
	v_cndmask_b32_e64 v32, v33, v32, s[42:43]
	v_cndmask_b32_e64 v33, v166, v162, s[42:43]
	v_add_f32_e32 v32, v32, v34
	v_add_f32_e32 v33, v33, v167
	v_cndmask_b32_e64 v34, v32, v33, s[44:45]
	s_nop 1
	v_mov_b32_dpp v34, v34 quad_perm:[3,2,1,0] row_mask:0xf bank_mask:0xf
	s_nop 1
	v_mov_b32_dpp v34, v34 row_half_mirror row_mask:0xf bank_mask:0xf
	v_cndmask_b32_e64 v32, v33, v32, s[44:45]
	s_mov_b32 s2, 0x3fb8aa3b
	s_waitcnt lgkmcnt(0)
	v_add_f32_e32 v32, v32, v34
	s_nop 1
	v_mov_b32_dpp v33, v32 quad_perm:[1,0,3,2] row_mask:0xf bank_mask:0xf
	s_waitcnt lgkmcnt(0)
	v_add_f32_e32 v32, v32, v33
	s_nop 1
	v_mov_b32_dpp v33, v32 quad_perm:[2,3,0,1] row_mask:0xf bank_mask:0xf
	s_waitcnt lgkmcnt(0)
	v_add_f32_e32 v32, v32, v33
	s_nop 1
	v_mov_b32_dpp v33, v32 quad_perm:[3,2,1,0] row_mask:0xf bank_mask:0xf
	s_nop 1
	v_mov_b32_dpp v33, v33 row_half_mirror row_mask:0xf bank_mask:0xf
	s_waitcnt lgkmcnt(0)
	v_max_f32_e32 v33, v33, v33
	v_max_f32_e32 v33, v32, v33
	s_nop 1
	v_mov_b32_dpp v34, v33 row_ror:8 row_mask:0xf bank_mask:0xf
	s_waitcnt lgkmcnt(0)
	v_max_f32_e32 v34, v34, v34
	v_max_f32_e32 v33, v33, v34
	v_mov_b32_e32 v34, v33
	s_nop 1
	v_permlane16_swap_b32 v34, v33
	s_waitcnt lgkmcnt(0)
	v_max_f32_e32 v34, v34, v34
	v_max_f32_e32 v33, v33, v34
	v_mov_b32_e32 v34, v33
	s_nop 1
	v_permlane32_swap_b32 v34, v33
	s_waitcnt lgkmcnt(0)
	v_max_f32_e32 v34, v34, v34
	v_max_f32_e32 v33, v33, v34
	v_sub_f32_e32 v32, v32, v33
	v_mul_f32_e32 v33, 0x3fb8aa3b, v32
	v_fma_f32 v34, v32, s2, -v33
	v_rndne_f32_e32 v140, v33
	v_fmac_f32_e32 v34, 0x32a5705f, v32
	v_sub_f32_e32 v33, v33, v140
	v_add_f32_e32 v33, v33, v34
	v_cvt_i32_f32_e32 v140, v140
	v_exp_f32_e32 v33, v33
	s_mov_b32 s2, 0xc2ce8ed0
	v_cmp_ngt_f32_e32 vcc, s2, v32
	s_mov_b32 s2, 0x42b17218
	v_ldexp_f32 v33, v33, v140
	v_cndmask_b32_e32 v33, 0, v33, vcc
	v_cmp_nlt_f32_e32 vcc, s2, v32
	s_nop 1
	v_cndmask_b32_e32 v32, v250, v33, vcc
	s_nop 1
	v_mov_b32_dpp v33, v32 quad_perm:[3,2,1,0] row_mask:0xf bank_mask:0xf
	s_nop 1
	v_mov_b32_dpp v33, v33 row_half_mirror row_mask:0xf bank_mask:0xf
	s_waitcnt lgkmcnt(0)
	v_add_f32_e32 v33, v32, v33
	s_nop 1
	v_mov_b32_dpp v34, v33 row_ror:8 row_mask:0xf bank_mask:0xf
	s_waitcnt lgkmcnt(0)
	v_add_f32_e32 v33, v33, v34
	v_mov_b32_e32 v34, v33
	s_nop 1
	v_permlane16_swap_b32 v34, v33
	s_waitcnt lgkmcnt(0)
	v_add_f32_e32 v33, v33, v34
	v_mov_b32_e32 v34, v33
	v_mov_b32_e32 v193, v33
	s_nop 1
	v_permlane32_swap_b32 v34, v193
	v_cndmask_b32_e64 v34, v34, v193, s[38:39]
	s_and_saveexec_b64 s[2:3], s[0:1]
	s_cbranch_execz .LBB0_844
	s_waitcnt lgkmcnt(0)
	v_add_f32_e32 v33, v33, v34
	v_div_scale_f32 v34, s[8:9], v33, v33, v32
	v_rcp_f32_e32 v140, v34
	v_div_scale_f32 v146, vcc, v32, v33, v32
	v_readlane_b32 s8, v254, 32
	v_fma_f32 v147, -v34, v140, 1.0
	v_fmac_f32_e32 v140, v147, v140
	v_mul_f32_e32 v147, v146, v140
	v_fma_f32 v148, -v34, v147, v146
	v_fmac_f32_e32 v147, v148, v140
	v_fma_f32 v34, -v34, v147, v146
	v_div_fmas_f32 v34, v34, v140, v147
	v_readlane_b32 s9, v254, 33
	v_div_fixup_f32 v34, v34, v33, v32
	s_nop 0
	v_lshl_add_u64 v[32:33], v[62:63], 0, s[8:9]
	flat_store_dword v[32:33], v34
.LBB0_844:
	s_or_b64 exec, exec, s[2:3]
	v_cndmask_b32_e64 v32, v36, v35, s[42:43]
	v_cndmask_b32_e64 v33, v156, v144, s[42:43]
	v_add_f32_e32 v32, v32, v37
	v_add_f32_e32 v33, v33, v163
	s_waitcnt lgkmcnt(0)
	v_cndmask_b32_e64 v34, v32, v33, s[44:45]
	s_nop 1
	v_mov_b32_dpp v34, v34 quad_perm:[3,2,1,0] row_mask:0xf bank_mask:0xf
	s_nop 1
	v_mov_b32_dpp v34, v34 row_half_mirror row_mask:0xf bank_mask:0xf
	v_cndmask_b32_e64 v32, v33, v32, s[44:45]
	s_mov_b32 s2, 0x3fb8aa3b
	s_waitcnt lgkmcnt(0)
	v_add_f32_e32 v32, v32, v34
	s_nop 1
	v_mov_b32_dpp v33, v32 quad_perm:[1,0,3,2] row_mask:0xf bank_mask:0xf
	s_waitcnt lgkmcnt(0)
	v_add_f32_e32 v32, v32, v33
	s_nop 1
	v_mov_b32_dpp v33, v32 quad_perm:[2,3,0,1] row_mask:0xf bank_mask:0xf
	s_waitcnt lgkmcnt(0)
	v_add_f32_e32 v32, v32, v33
	s_nop 1
	v_mov_b32_dpp v33, v32 quad_perm:[3,2,1,0] row_mask:0xf bank_mask:0xf
	s_nop 1
	v_mov_b32_dpp v33, v33 row_half_mirror row_mask:0xf bank_mask:0xf
	s_waitcnt lgkmcnt(0)
	v_max_f32_e32 v33, v33, v33
	v_max_f32_e32 v33, v32, v33
	s_nop 1
	v_mov_b32_dpp v34, v33 row_ror:8 row_mask:0xf bank_mask:0xf
	s_waitcnt lgkmcnt(0)
	v_max_f32_e32 v34, v34, v34
	v_max_f32_e32 v33, v33, v34
	v_mov_b32_e32 v34, v33
	s_nop 1
	v_permlane16_swap_b32 v34, v33
	s_waitcnt lgkmcnt(0)
	v_max_f32_e32 v34, v34, v34
	v_max_f32_e32 v33, v33, v34
	v_mov_b32_e32 v34, v33
	s_nop 1
	v_permlane32_swap_b32 v34, v33
	s_waitcnt lgkmcnt(0)
	v_max_f32_e32 v34, v34, v34
	v_max_f32_e32 v33, v33, v34
	v_sub_f32_e32 v32, v32, v33
	v_mul_f32_e32 v33, 0x3fb8aa3b, v32
	v_fma_f32 v34, v32, s2, -v33
	v_rndne_f32_e32 v35, v33
	v_fmac_f32_e32 v34, 0x32a5705f, v32
	v_sub_f32_e32 v33, v33, v35
	v_add_f32_e32 v33, v33, v34
	v_cvt_i32_f32_e32 v35, v35
	v_exp_f32_e32 v33, v33
	s_mov_b32 s2, 0xc2ce8ed0
	v_cmp_ngt_f32_e32 vcc, s2, v32
	s_mov_b32 s2, 0x42b17218
	v_ldexp_f32 v33, v33, v35
	v_cndmask_b32_e32 v33, 0, v33, vcc
	v_cmp_nlt_f32_e32 vcc, s2, v32
	s_nop 1
	v_cndmask_b32_e32 v32, v250, v33, vcc
	s_nop 1
	v_mov_b32_dpp v33, v32 quad_perm:[3,2,1,0] row_mask:0xf bank_mask:0xf
	s_nop 1
	v_mov_b32_dpp v33, v33 row_half_mirror row_mask:0xf bank_mask:0xf
	s_waitcnt lgkmcnt(0)
	v_add_f32_e32 v33, v32, v33
	s_nop 1
	v_mov_b32_dpp v34, v33 row_ror:8 row_mask:0xf bank_mask:0xf
	s_waitcnt lgkmcnt(0)
	v_add_f32_e32 v33, v33, v34
	v_mov_b32_e32 v34, v33
	s_nop 1
	v_permlane16_swap_b32 v34, v33
	s_waitcnt lgkmcnt(0)
	v_add_f32_e32 v33, v33, v34
	v_mov_b32_e32 v34, v33
	v_mov_b32_e32 v190, v33
	s_nop 1
	v_permlane32_swap_b32 v34, v190
	v_cndmask_b32_e64 v34, v34, v190, s[38:39]
	s_and_saveexec_b64 s[2:3], s[0:1]
	s_cbranch_execz .LBB0_846
	s_waitcnt lgkmcnt(0)
	v_add_f32_e32 v33, v33, v34
	v_div_scale_f32 v34, s[8:9], v33, v33, v32
	v_rcp_f32_e32 v35, v34
	v_div_scale_f32 v36, vcc, v32, v33, v32
	v_readlane_b32 s8, v254, 36
	v_fma_f32 v37, -v34, v35, 1.0
	v_fmac_f32_e32 v35, v37, v35
	v_mul_f32_e32 v37, v36, v35
	v_fma_f32 v140, -v34, v37, v36
	v_fmac_f32_e32 v37, v140, v35
	v_fma_f32 v34, -v34, v37, v36
	v_div_fmas_f32 v34, v34, v35, v37
	v_readlane_b32 s9, v254, 37
	v_div_fixup_f32 v34, v34, v33, v32
	s_nop 0
	v_lshl_add_u64 v[32:33], v[62:63], 0, s[8:9]
	flat_store_dword v[32:33], v34
; __device__ __forceinline__ float shx(float v, int o, int lane) { return __builtin_bit_cast(float, __builtin_amdgcn_ds_bpermute((lane ^ o) << 2, __builtin_bit_cast(int, v))); }
; __device__ __forceinline__ void phase_ma(const Params& p, Frame& F, int l, const bool fd, const float* xin32) {
;     ...
;         for (int r = 0; r < 4; ++r) { float t1;
;             { const bool hi = (F.lane & 4) != 0; const float send = hi ? th2[r][0] : th2[r][1], keep = hi ? th2[r][1] : th2[r][0]; t1 = keep + shx(send, 4, F.lane); }
;             t1 += shx(t1, 1, F.lane); t1 += shx(t1, 2, F.lane);
;             float mx = t1;
; #pragma unroll
;             for (int o = 4; o < 64; o <<= 1) mx = fmaxf(mx, shx(mx, o, F.lane));
;             const float pe = expf(t1 - mx); float sum = pe;
; #pragma unroll
;             for (int o = 4; o < 64; o <<= 1) sum += shx(sum, o, F.lane);
;             const int e = ((F.lane >> 2) & 1) * 8 + ((F.lane >> 5) & 1) * 4 + ((F.lane >> 4) & 1) * 2 + ((F.lane >> 3) & 1);
;             if ((F.lane & 3) == 0) aff[((size_t)b * NE + e) * S + s0 + r * rstep] = pe / sum; }
.LBB0_846:
	s_or_b64 exec, exec, s[2:3]
	v_cndmask_b32_e64 v32, v39, v38, s[42:43]
	v_cndmask_b32_e64 v33, v142, v141, s[42:43]
	v_add_f32_e32 v32, v32, v139
	v_add_f32_e32 v33, v33, v143
	s_waitcnt lgkmcnt(0)
	v_cndmask_b32_e64 v34, v32, v33, s[44:45]
	s_nop 1
	v_mov_b32_dpp v34, v34 quad_perm:[3,2,1,0] row_mask:0xf bank_mask:0xf
	s_nop 1
	v_mov_b32_dpp v34, v34 row_half_mirror row_mask:0xf bank_mask:0xf
	v_cndmask_b32_e64 v32, v33, v32, s[44:45]
	s_mov_b32 s2, 0x3fb8aa3b
	s_waitcnt lgkmcnt(0)
	v_add_f32_e32 v32, v32, v34
	s_nop 1
	v_mov_b32_dpp v33, v32 quad_perm:[1,0,3,2] row_mask:0xf bank_mask:0xf
	s_waitcnt lgkmcnt(0)
	v_add_f32_e32 v32, v32, v33
	s_nop 1
	v_mov_b32_dpp v33, v32 quad_perm:[2,3,0,1] row_mask:0xf bank_mask:0xf
	s_waitcnt lgkmcnt(0)
	v_add_f32_e32 v32, v32, v33
	s_nop 1
	v_mov_b32_dpp v33, v32 quad_perm:[3,2,1,0] row_mask:0xf bank_mask:0xf
	s_nop 1
	v_mov_b32_dpp v33, v33 row_half_mirror row_mask:0xf bank_mask:0xf
	s_waitcnt lgkmcnt(0)
	v_max_f32_e32 v33, v33, v33
	v_max_f32_e32 v33, v32, v33
	s_nop 1
	v_mov_b32_dpp v34, v33 row_ror:8 row_mask:0xf bank_mask:0xf
	s_waitcnt lgkmcnt(0)
	v_max_f32_e32 v34, v34, v34
	v_max_f32_e32 v33, v33, v34
	v_mov_b32_e32 v34, v33
	s_nop 1
	v_permlane16_swap_b32 v34, v33
	s_waitcnt lgkmcnt(0)
	v_max_f32_e32 v34, v34, v34
	v_max_f32_e32 v33, v33, v34
	v_mov_b32_e32 v34, v33
	s_nop 1
	v_permlane32_swap_b32 v34, v33
	s_waitcnt lgkmcnt(0)
	v_max_f32_e32 v34, v34, v34
	v_max_f32_e32 v33, v33, v34
	v_sub_f32_e32 v32, v32, v33
	v_mul_f32_e32 v33, 0x3fb8aa3b, v32
	v_fma_f32 v34, v32, s2, -v33
	v_rndne_f32_e32 v35, v33
	v_fmac_f32_e32 v34, 0x32a5705f, v32
	v_sub_f32_e32 v33, v33, v35
	v_add_f32_e32 v33, v33, v34
	v_cvt_i32_f32_e32 v35, v35
	v_exp_f32_e32 v33, v33
	s_mov_b32 s2, 0xc2ce8ed0
	v_cmp_ngt_f32_e32 vcc, s2, v32
	s_mov_b32 s2, 0x42b17218
	v_ldexp_f32 v33, v33, v35
	v_cndmask_b32_e32 v33, 0, v33, vcc
	v_cmp_nlt_f32_e32 vcc, s2, v32
	s_nop 1
	v_cndmask_b32_e32 v32, v250, v33, vcc
	s_nop 1
	v_mov_b32_dpp v33, v32 quad_perm:[3,2,1,0] row_mask:0xf bank_mask:0xf
	s_nop 1
	v_mov_b32_dpp v33, v33 row_half_mirror row_mask:0xf bank_mask:0xf
	s_waitcnt lgkmcnt(0)
	v_add_f32_e32 v33, v32, v33
	s_nop 1
	v_mov_b32_dpp v34, v33 row_ror:8 row_mask:0xf bank_mask:0xf
	s_waitcnt lgkmcnt(0)
	v_add_f32_e32 v33, v33, v34
	v_mov_b32_e32 v34, v33
	s_nop 1
	v_permlane16_swap_b32 v34, v33
	s_waitcnt lgkmcnt(0)
	v_add_f32_e32 v33, v33, v34
	v_mov_b32_e32 v34, v33
	v_mov_b32_e32 v191, v33
	s_nop 1
	v_permlane32_swap_b32 v34, v191
	v_cndmask_b32_e64 v34, v34, v191, s[38:39]
	s_and_saveexec_b64 s[2:3], s[0:1]
	s_cbranch_execz .LBB0_611
	s_waitcnt lgkmcnt(0)
	v_add_f32_e32 v33, v33, v34
	v_div_scale_f32 v34, s[8:9], v33, v33, v32
	v_rcp_f32_e32 v35, v34
	v_div_scale_f32 v36, vcc, v32, v33, v32
	v_readlane_b32 s8, v254, 40
	v_fma_f32 v37, -v34, v35, 1.0
	v_fmac_f32_e32 v35, v37, v35
	v_mul_f32_e32 v37, v36, v35
	v_fma_f32 v38, -v34, v37, v36
	v_fmac_f32_e32 v37, v38, v35
	v_fma_f32 v34, -v34, v37, v36
	v_div_fmas_f32 v34, v34, v35, v37
	v_readlane_b32 s9, v254, 41
	v_div_fixup_f32 v34, v34, v33, v32
	s_nop 0
	v_lshl_add_u64 v[32:33], v[62:63], 0, s[8:9]
	flat_store_dword v[32:33], v34
	s_branch .LBB0_611
